# speedup vs baseline: 1.0104x; 1.0047x over previous
; #define GAS __attribute__((address_space(1)))
; #define WAIT_V(n) asm volatile("s_waitcnt vmcnt(" #n ")" ::: "memory")
; #define BAR __builtin_amdgcn_s_barrier()
; template <int K, int LD = K>
; __device__ __forceinline__ void gemm_main(const GAS bf16* A, const GAS bf16* Bt, int brow, int bcol, f32x4 (&acc)[2][2][4][2]) {
;     ...
;   const int wid = tid_ >> 6, lane = tid_ & 63, wr = wid >> 2, wc = wid & 3, fr = lane & 15, fq = lane >> 4;
; #pragma unroll
;   for (int a = 0; a < 2; ++a)
; #pragma unroll
;     for (int b = 0; b < 2; ++b)
; #pragma unroll
;       for (int m = 0; m < 4; ++m)
; #pragma unroll
;         for (int n = 0; n < 2; ++n) acc[a][b][m][n] = f32x4{0.f, 0.f, 0.f, 0.f};
;   bf16x8 At[4][2], B0[2][2], B1[2][2];
;   unsigned so0, so1;
;   { int r_, c_; stage_rc(tid_ * 16, r_, c_); so0 = (unsigned)(r_ * LD + c_) * 2u; stage_rc(tid_ * 16 + 8192, r_, c_); so1 = (unsigned)(r_ * LD + c_) * 2u; }
;   const GAS char* pA0 = (const GAS char*)A + (long)brow * LD * 2; const GAS char* pA1 = pA0 + (long)HALF * LD * 2;
;   const GAS char* pB0 = (const GAS char*)Bt + (long)bcol * LD * 2; const GAS char* pB1 = pB0 + (long)HALF * LD * 2;
;   asm volatile("" : "+s"(pA0), "+s"(pA1), "+s"(pB0), "+s"(pB1));
;   constexpr int nt = K / BK;
;   static_assert(K % 128 == 0 && K >= 256, "K");
;   if (wr == 1) BAR;
;   WAIT_V(0); BAR;
;   BAR;
.LBB0_88:
	s_or_b64 exec, exec, s[24:25]
	v_bfe_i32 v7, v136, 27, 1
	v_lshlrev_b32_e32 v5, 4, v136
	v_lshrrev_b32_e32 v7, 22, v7
	v_add_u32_e32 v7, v5, v7
	v_and_b32_e32 v7, 0xfffffc00, v7
	v_sub_u32_e32 v7, v5, v7
	v_lshrrev_b32_e32 v8, 4, v7
	v_bitop3_b32 v8, v8, v7, 32 bitop3:0x6c
	v_ashrrev_i32_e32 v7, 31, v7
	v_ashrrev_i32_e32 v6, 31, v136
	v_lshrrev_b32_e32 v7, 26, v7
	v_lshrrev_b32_e32 v6, 26, v6
	v_add_u32_e32 v7, v8, v7
	v_add_u32_e32 v6, v136, v6
	v_ashrrev_i32_e32 v7, 6, v7
	v_ashrrev_i32_e32 v6, 6, v6
	v_mul_i32_i24_e32 v10, 64, v7
	v_lshlrev_b32_e32 v9, 3, v6
	v_lshlrev_b32_e32 v6, 5, v6
	v_sub_u32_e32 v8, v8, v10
	v_and_b32_e32 v9, 0x1ffff0, v9
	v_and_b32_e32 v6, 32, v6
	v_ashrrev_i16_sdwa v8, v134, sext(v8) dst_sel:DWORD dst_unused:UNUSED_PAD src0_sel:DWORD src1_sel:BYTE_0
	v_add_u32_sdwa v6, v6, sext(v8) dst_sel:DWORD dst_unused:UNUSED_PAD src0_sel:DWORD src1_sel:WORD_0
	v_add_lshl_u32 v7, v7, v9, 11
	v_lshl_add_u32 v130, v6, 1, v7
	v_add_u32_e32 v6, 0x2000, v5
	v_ashrrev_i32_e32 v7, 31, v6
	v_lshrrev_b32_e32 v7, 22, v7
	v_add_u32_e32 v7, v6, v7
	v_ashrrev_i32_e32 v7, 10, v7
	v_mul_i32_i24_e32 v8, 0x400, v7
	v_sub_u32_e32 v6, v6, v8
	v_lshrrev_b32_e32 v8, 4, v6
	v_bitop3_b32 v6, v8, v6, 32 bitop3:0x6c
	v_ashrrev_i32_e32 v9, 31, v6
	v_lshrrev_b32_e32 v9, 26, v9
	v_add_u32_e32 v9, v6, v9
	v_lshrrev_b32_e32 v10, 6, v9
	v_and_b32_e32 v9, 0xc0, v9
	v_lshlrev_b32_e32 v8, 3, v7
	v_lshlrev_b32_e32 v7, 5, v7
	v_sub_u32_e32 v6, v6, v9
	v_and_b32_e32 v8, 0x1ffff0, v8
	v_and_b32_e32 v7, 32, v7
	v_ashrrev_i16_sdwa v6, v134, sext(v6) dst_sel:DWORD dst_unused:UNUSED_PAD src0_sel:DWORD src1_sel:BYTE_0
	v_add_u32_sdwa v6, v7, sext(v6) dst_sel:DWORD dst_unused:UNUSED_PAD src0_sel:DWORD src1_sel:WORD_0
	v_add_lshl_u32 v7, v10, v8, 11
	v_and_b32_e32 v3, 15, v136
	v_lshl_add_u32 v132, v6, 1, v7
	v_lshlrev_b32_e32 v6, 2, v136
	v_and_b32_e32 v4, 48, v136
	v_lshlrev_b32_e32 v3, 6, v3
	v_and_b32_e32 v6, 32, v6
	v_lshlrev_b32_e32 v11, 6, v136
	v_bitop3_b32 v3, v3, v6, v4 bitop3:0x36
	v_lshlrev_b32_e32 v13, 13, v2
	v_and_or_b32 v2, v11, s38, v4
	v_add_u32_e32 v7, s29, v3
	v_add_u32_e32 v8, s30, v3
	v_add_u32_e32 v9, s31, v3
	v_add_u32_e32 v10, s33, v3
	v_and_b32_e32 v12, 0x3000, v11
	v_add_u32_e32 v3, 0x100, v3
	v_xad_u32 v4, v2, v6, s34
	v_or_b32_e32 v6, 0x800, v13
	v_or_b32_e32 v11, 0x1000, v13
	v_or_b32_e32 v14, 0x1800, v13
	v_mov_b32_e32 v2, 0
	v_add_u32_e32 v145, 0x100, v5
	v_add_u32_e32 v146, s29, v5
	v_add_u32_e32 v147, s30, v5
	v_add_u32_e32 v148, s31, v5
	v_add_u32_e32 v149, s33, v5
	v_mov_b32_e32 v133, v131
	s_mov_b32 s17, -2
	v_add_u32_e32 v144, v7, v12
	v_add_u32_e32 v140, v3, v13
	v_add_u32_e32 v139, v4, v6
	v_add_u32_e32 v138, v4, v11
	v_add_u32_e32 v137, v4, v14
	v_add_u32_e32 v143, v8, v12
	v_add_u32_e32 v142, v9, v12
	v_add_u32_e32 v141, v10, v12
	v_mov_b32_e32 v3, v2
	v_mov_b32_e32 v4, v2
	v_mov_b32_e32 v5, v2
	v_mov_b32_e32 v6, v2
	v_mov_b32_e32 v7, v2
	v_mov_b32_e32 v8, v2
	v_mov_b32_e32 v9, v2
	v_mov_b32_e32 v10, v2
	v_mov_b32_e32 v11, v2
	v_mov_b32_e32 v12, v2
	v_mov_b32_e32 v13, v2
	v_mov_b32_e32 v14, v2
	v_mov_b32_e32 v15, v2
	v_mov_b32_e32 v16, v2
	v_mov_b32_e32 v17, v2
	v_mov_b32_e32 v18, v2
	v_mov_b32_e32 v19, v2
	v_mov_b32_e32 v20, v2
	v_mov_b32_e32 v21, v2
	v_mov_b32_e32 v22, v2
	v_mov_b32_e32 v23, v2
	v_mov_b32_e32 v24, v2
	v_mov_b32_e32 v25, v2
	v_mov_b32_e32 v26, v2
	v_mov_b32_e32 v27, v2
	v_mov_b32_e32 v28, v2
	v_mov_b32_e32 v29, v2
	v_mov_b32_e32 v30, v2
	v_mov_b32_e32 v31, v2
	v_mov_b32_e32 v32, v2
	v_mov_b32_e32 v33, v2
	v_mov_b32_e32 v34, v2
	v_mov_b32_e32 v35, v2
	v_mov_b32_e32 v36, v2
	v_mov_b32_e32 v37, v2
	v_mov_b32_e32 v38, v2
	v_mov_b32_e32 v39, v2
	v_mov_b32_e32 v40, v2
	v_mov_b32_e32 v41, v2
	v_mov_b32_e32 v42, v2
	v_mov_b32_e32 v43, v2
	v_mov_b32_e32 v44, v2
	v_mov_b32_e32 v45, v2
	v_mov_b32_e32 v46, v2
	v_mov_b32_e32 v47, v2
	v_mov_b32_e32 v48, v2
	v_mov_b32_e32 v49, v2
	v_mov_b32_e32 v50, v2
	v_mov_b32_e32 v51, v2
	v_mov_b32_e32 v52, v2
	v_mov_b32_e32 v53, v2
	v_mov_b32_e32 v54, v2
	v_mov_b32_e32 v55, v2
	v_mov_b32_e32 v56, v2
	v_mov_b32_e32 v57, v2
	v_mov_b32_e32 v58, v2
	v_mov_b32_e32 v59, v2
	v_mov_b32_e32 v60, v2
	v_mov_b32_e32 v61, v2
	v_mov_b32_e32 v62, v2
	v_mov_b32_e32 v63, v2
	v_mov_b32_e32 v64, v2
	v_mov_b32_e32 v65, v2
	v_mov_b32_e32 v66, v2
	v_mov_b32_e32 v67, v2
	v_mov_b32_e32 v68, v2
	v_mov_b32_e32 v69, v2
	v_mov_b32_e32 v70, v2
	v_mov_b32_e32 v71, v2
	v_mov_b32_e32 v72, v2
	v_mov_b32_e32 v73, v2
	v_mov_b32_e32 v74, v2
	v_mov_b32_e32 v75, v2
	v_mov_b32_e32 v76, v2
	v_mov_b32_e32 v77, v2
	v_mov_b32_e32 v78, v2
	v_mov_b32_e32 v79, v2
	v_mov_b32_e32 v80, v2
	v_mov_b32_e32 v81, v2
	v_mov_b32_e32 v82, v2
	v_mov_b32_e32 v83, v2
	v_mov_b32_e32 v84, v2
	v_mov_b32_e32 v85, v2
	v_mov_b32_e32 v86, v2
	v_mov_b32_e32 v87, v2
	v_mov_b32_e32 v88, v2
	v_mov_b32_e32 v89, v2
	v_mov_b32_e32 v90, v2
	v_mov_b32_e32 v91, v2
	v_mov_b32_e32 v92, v2
	v_mov_b32_e32 v93, v2
	v_mov_b32_e32 v94, v2
	v_mov_b32_e32 v95, v2
	v_mov_b32_e32 v96, v2
	v_mov_b32_e32 v97, v2
	v_mov_b32_e32 v98, v2
	v_mov_b32_e32 v99, v2
	v_mov_b32_e32 v100, v2
	v_mov_b32_e32 v101, v2
	v_mov_b32_e32 v102, v2
	v_mov_b32_e32 v103, v2
	v_mov_b32_e32 v104, v2
	v_mov_b32_e32 v105, v2
	v_mov_b32_e32 v106, v2
	v_mov_b32_e32 v107, v2
	v_mov_b32_e32 v108, v2
	v_mov_b32_e32 v109, v2
	v_mov_b32_e32 v110, v2
	v_mov_b32_e32 v111, v2
	v_mov_b32_e32 v112, v2
	v_mov_b32_e32 v113, v2
	v_mov_b32_e32 v114, v2
	v_mov_b32_e32 v115, v2
	v_mov_b32_e32 v116, v2
	v_mov_b32_e32 v117, v2
	v_mov_b32_e32 v118, v2
	v_mov_b32_e32 v119, v2
	v_mov_b32_e32 v120, v2
	v_mov_b32_e32 v121, v2
	v_mov_b32_e32 v122, v2
	v_mov_b32_e32 v123, v2
	v_mov_b32_e32 v124, v2
	v_mov_b32_e32 v125, v2
	v_mov_b32_e32 v126, v2
	v_mov_b32_e32 v127, v2
	v_mov_b32_e32 v128, v2
	v_mov_b32_e32 v129, v2
	v_add_u32_e32 v151, 0xc000, v145
	v_add_u32_e32 v150, 0xe000, v145
	v_add_u32_e32 v152, 0x2000, v145
	v_add_u32_e32 v153, 0x4000, v145
	v_add_u32_e32 v154, 0x6000, v145
	v_add_u32_e32 v155, 0x8000, v145
	v_add_u32_e32 v156, 0xa000, v145
	v_add_u32_e32 v157, 0x2000, v146
	v_add_u32_e32 v158, 0x2000, v147
	v_add_u32_e32 v159, 0x2000, v148
	v_add_u32_e32 v160, 0x2000, v149
	s_waitcnt vmcnt(0)
	s_barrier
	s_barrier
	.p2align 6

; #define GAS __attribute__((address_space(1)))
; #define WAIT_V(n) asm volatile("s_waitcnt vmcnt(" #n ")" ::: "memory")
; #define BAR __builtin_amdgcn_s_barrier()
; template <int K, int LD = K>
; __device__ __forceinline__ void gemm_main(const GAS bf16* A, const GAS bf16* Bt, int brow, int bcol, f32x4 (&acc)[2][2][4][2]) {
;     ...
;   const int wid = tid_ >> 6, lane = tid_ & 63, wr = wid >> 2, wc = wid & 3, fr = lane & 15, fq = lane >> 4;
; #pragma unroll
;   for (int a = 0; a < 2; ++a)
; #pragma unroll
;     for (int b = 0; b < 2; ++b)
; #pragma unroll
;       for (int m = 0; m < 4; ++m)
; #pragma unroll
;         for (int n = 0; n < 2; ++n) acc[a][b][m][n] = f32x4{0.f, 0.f, 0.f, 0.f};
;   bf16x8 At[4][2], B0[2][2], B1[2][2];
;   unsigned so0, so1;
;   { int r_, c_; stage_rc(tid_ * 16, r_, c_); so0 = (unsigned)(r_ * LD + c_) * 2u; stage_rc(tid_ * 16 + 8192, r_, c_); so1 = (unsigned)(r_ * LD + c_) * 2u; }
;   const GAS char* pA0 = (const GAS char*)A + (long)brow * LD * 2; const GAS char* pA1 = pA0 + (long)HALF * LD * 2;
;   const GAS char* pB0 = (const GAS char*)Bt + (long)bcol * LD * 2; const GAS char* pB1 = pB0 + (long)HALF * LD * 2;
;   asm volatile("" : "+s"(pA0), "+s"(pA1), "+s"(pB0), "+s"(pB1));
;   constexpr int nt = K / BK;
;   static_assert(K % 128 == 0 && K >= 256, "K");
;   if (wr == 1) BAR;
;   WAIT_V(0); BAR;
;   BAR;
.LBB0_229:
	s_or_b64 exec, exec, s[22:23]
	v_bfe_i32 v7, v134, 27, 1
	v_lshlrev_b32_e32 v5, 4, v134
	v_lshrrev_b32_e32 v7, 22, v7
	v_add_u32_e32 v7, v5, v7
	v_and_b32_e32 v7, 0xfffffc00, v7
	v_ashrrev_i32_e32 v6, 31, v134
	v_sub_u32_e32 v7, v5, v7
	v_lshrrev_b32_e32 v6, 26, v6
	v_lshrrev_b32_e32 v8, 4, v7
	v_add_u32_e32 v6, v134, v6
	v_bitop3_b32 v8, v8, v7, 32 bitop3:0x6c
	v_ashrrev_i32_e32 v7, 31, v7
	v_ashrrev_i32_e32 v6, 6, v6
	v_lshrrev_b32_e32 v7, 26, v7
	v_lshlrev_b32_e32 v9, 3, v6
	v_add_u32_e32 v7, v8, v7
	v_and_b32_e32 v9, 0x3fffff0, v9
	v_ashrrev_i32_e32 v7, 6, v7
	v_add_u32_e32 v9, v7, v9
	v_mul_i32_i24_e32 v7, 64, v7
	v_sub_u32_e32 v7, v8, v7
	v_lshlrev_b32_e32 v6, 5, v6
	v_ashrrev_i16_sdwa v7, v154, sext(v7) dst_sel:DWORD dst_unused:UNUSED_PAD src0_sel:DWORD src1_sel:BYTE_0
	v_mul_lo_u32 v8, v9, s34
	v_bfe_i32 v7, v7, 0, 16
	v_and_or_b32 v6, v6, 32, v8
	v_add_lshl_u32 v130, v6, v7, 1
	v_add_u32_e32 v6, 0x2000, v5
	v_ashrrev_i32_e32 v7, 31, v6
	v_lshrrev_b32_e32 v7, 22, v7
	v_add_u32_e32 v7, v6, v7
	v_ashrrev_i32_e32 v7, 10, v7
	v_mul_i32_i24_e32 v8, 0x400, v7
	v_sub_u32_e32 v6, v6, v8
	v_lshrrev_b32_e32 v8, 4, v6
	v_bitop3_b32 v6, v8, v6, 32 bitop3:0x6c
	v_ashrrev_i32_e32 v9, 31, v6
	v_lshrrev_b32_e32 v9, 26, v9
	v_lshlrev_b32_e32 v8, 3, v7
	v_add_u32_e32 v9, v6, v9
	v_and_b32_e32 v8, 0x3fffff0, v8
	v_lshrrev_b32_e32 v10, 6, v9
	v_and_b32_e32 v9, 0xc0, v9
	v_add_u32_e32 v8, v10, v8
	v_sub_u32_e32 v6, v6, v9
	v_lshlrev_b32_e32 v7, 5, v7
	v_ashrrev_i16_sdwa v6, v154, sext(v6) dst_sel:DWORD dst_unused:UNUSED_PAD src0_sel:DWORD src1_sel:BYTE_0
	v_mul_lo_u32 v8, v8, s34
	v_bfe_i32 v6, v6, 0, 16
	v_and_or_b32 v7, v7, 32, v8
	v_and_b32_e32 v3, 15, v134
	v_add_lshl_u32 v132, v7, v6, 1
	v_lshlrev_b32_e32 v6, 2, v134
	v_and_b32_e32 v4, 48, v134
	v_lshlrev_b32_e32 v3, 6, v3
	v_and_b32_e32 v6, 32, v6
	v_lshlrev_b32_e32 v11, 6, v134
	v_bitop3_b32 v3, v3, v6, v4 bitop3:0x36
	v_lshlrev_b32_e32 v13, 13, v2
	v_and_or_b32 v2, v11, s40, v4
	v_add_u32_e32 v7, s36, v3
	v_add_u32_e32 v8, s37, v3
	v_add_u32_e32 v9, s38, v3
	v_add_u32_e32 v10, s39, v3
	v_and_b32_e32 v12, 0x3000, v11
	v_add_u32_e32 v3, 0x100, v3
	v_xad_u32 v4, v2, v6, s35
	v_or_b32_e32 v6, 0x800, v13
	v_or_b32_e32 v11, 0x1000, v13
	v_or_b32_e32 v14, 0x1800, v13
	v_mov_b32_e32 v2, 0
	v_add_u32_e32 v145, 0x100, v5
	v_add_u32_e32 v151, s36, v5
	v_add_u32_e32 v153, s37, v5
	v_add_u32_e32 v156, s38, v5
	v_add_u32_e32 v158, s39, v5
	v_mov_b32_e32 v133, v131
	s_mov_b32 s22, -2
	v_add_u32_e32 v144, v7, v12
	v_add_u32_e32 v138, v3, v13
	v_add_u32_e32 v137, v4, v6
	v_add_u32_e32 v136, v4, v11
	v_add_u32_e32 v135, v4, v14
	v_add_u32_e32 v143, 0xc000, v145
	v_add_u32_e32 v142, 0xe000, v145
	v_add_u32_e32 v141, v8, v12
	v_add_u32_e32 v146, 0x2000, v145
	v_add_u32_e32 v140, v9, v12
	v_add_u32_e32 v147, 0x4000, v145
	v_add_u32_e32 v148, 0x6000, v145
	v_add_u32_e32 v139, v10, v12
	v_add_u32_e32 v149, 0x8000, v145
	v_add_u32_e32 v150, 0xa000, v145
	v_add_u32_e32 v152, 0x2000, v151
	v_add_u32_e32 v155, 0x2000, v153
	v_add_u32_e32 v157, 0x2000, v156
	v_add_u32_e32 v159, 0x2000, v158
	v_mov_b32_e32 v3, v2
	v_mov_b32_e32 v4, v2
	v_mov_b32_e32 v5, v2
	v_mov_b32_e32 v6, v2
	v_mov_b32_e32 v7, v2
	v_mov_b32_e32 v8, v2
	v_mov_b32_e32 v9, v2
	v_mov_b32_e32 v10, v2
	v_mov_b32_e32 v11, v2
	v_mov_b32_e32 v12, v2
	v_mov_b32_e32 v13, v2
	v_mov_b32_e32 v14, v2
	v_mov_b32_e32 v15, v2
	v_mov_b32_e32 v16, v2
	v_mov_b32_e32 v17, v2
	v_mov_b32_e32 v18, v2
	v_mov_b32_e32 v19, v2
	v_mov_b32_e32 v20, v2
	v_mov_b32_e32 v21, v2
	v_mov_b32_e32 v22, v2
	v_mov_b32_e32 v23, v2
	v_mov_b32_e32 v24, v2
	v_mov_b32_e32 v25, v2
	v_mov_b32_e32 v26, v2
	v_mov_b32_e32 v27, v2
	v_mov_b32_e32 v28, v2
	v_mov_b32_e32 v29, v2
	v_mov_b32_e32 v30, v2
	v_mov_b32_e32 v31, v2
	v_mov_b32_e32 v32, v2
	v_mov_b32_e32 v33, v2
	v_mov_b32_e32 v34, v2
	v_mov_b32_e32 v35, v2
	v_mov_b32_e32 v36, v2
	v_mov_b32_e32 v37, v2
	v_mov_b32_e32 v38, v2
	v_mov_b32_e32 v39, v2
	v_mov_b32_e32 v40, v2
	v_mov_b32_e32 v41, v2
	v_mov_b32_e32 v42, v2
	v_mov_b32_e32 v43, v2
	v_mov_b32_e32 v44, v2
	v_mov_b32_e32 v45, v2
	v_mov_b32_e32 v46, v2
	v_mov_b32_e32 v47, v2
	v_mov_b32_e32 v48, v2
	v_mov_b32_e32 v49, v2
	v_mov_b32_e32 v50, v2
	v_mov_b32_e32 v51, v2
	v_mov_b32_e32 v52, v2
	v_mov_b32_e32 v53, v2
	v_mov_b32_e32 v54, v2
	v_mov_b32_e32 v55, v2
	v_mov_b32_e32 v56, v2
	v_mov_b32_e32 v57, v2
	v_mov_b32_e32 v58, v2
	v_mov_b32_e32 v59, v2
	v_mov_b32_e32 v60, v2
	v_mov_b32_e32 v61, v2
	v_mov_b32_e32 v62, v2
	v_mov_b32_e32 v63, v2
	v_mov_b32_e32 v64, v2
	v_mov_b32_e32 v65, v2
	v_mov_b32_e32 v66, v2
	v_mov_b32_e32 v67, v2
	v_mov_b32_e32 v68, v2
	v_mov_b32_e32 v69, v2
	v_mov_b32_e32 v70, v2
	v_mov_b32_e32 v71, v2
	v_mov_b32_e32 v72, v2
	v_mov_b32_e32 v73, v2
	v_mov_b32_e32 v74, v2
	v_mov_b32_e32 v75, v2
	v_mov_b32_e32 v76, v2
	v_mov_b32_e32 v77, v2
	v_mov_b32_e32 v78, v2
	v_mov_b32_e32 v79, v2
	v_mov_b32_e32 v80, v2
	v_mov_b32_e32 v81, v2
	v_mov_b32_e32 v82, v2
	v_mov_b32_e32 v83, v2
	v_mov_b32_e32 v84, v2
	v_mov_b32_e32 v85, v2
	v_mov_b32_e32 v86, v2
	v_mov_b32_e32 v87, v2
	v_mov_b32_e32 v88, v2
	v_mov_b32_e32 v89, v2
	v_mov_b32_e32 v90, v2
	v_mov_b32_e32 v91, v2
	v_mov_b32_e32 v92, v2
	v_mov_b32_e32 v93, v2
	v_mov_b32_e32 v94, v2
	v_mov_b32_e32 v95, v2
	v_mov_b32_e32 v96, v2
	v_mov_b32_e32 v97, v2
	v_mov_b32_e32 v98, v2
	v_mov_b32_e32 v99, v2
	v_mov_b32_e32 v100, v2
	v_mov_b32_e32 v101, v2
	v_mov_b32_e32 v102, v2
	v_mov_b32_e32 v103, v2
	v_mov_b32_e32 v104, v2
	v_mov_b32_e32 v105, v2
	v_mov_b32_e32 v106, v2
	v_mov_b32_e32 v107, v2
	v_mov_b32_e32 v108, v2
	v_mov_b32_e32 v109, v2
	v_mov_b32_e32 v110, v2
	v_mov_b32_e32 v111, v2
	v_mov_b32_e32 v112, v2
	v_mov_b32_e32 v113, v2
	v_mov_b32_e32 v114, v2
	v_mov_b32_e32 v115, v2
	v_mov_b32_e32 v116, v2
	v_mov_b32_e32 v117, v2
	v_mov_b32_e32 v118, v2
	v_mov_b32_e32 v119, v2
	v_mov_b32_e32 v120, v2
	v_mov_b32_e32 v121, v2
	v_mov_b32_e32 v122, v2
	v_mov_b32_e32 v123, v2
	v_mov_b32_e32 v124, v2
	v_mov_b32_e32 v125, v2
	v_mov_b32_e32 v126, v2
	v_mov_b32_e32 v127, v2
	v_mov_b32_e32 v128, v2
	v_mov_b32_e32 v129, v2
	s_waitcnt vmcnt(0)
	s_barrier
	s_barrier
	.p2align 6

; #define GAS __attribute__((address_space(1)))
; #define WAIT_V(n) asm volatile("s_waitcnt vmcnt(" #n ")" ::: "memory")
; #define BAR __builtin_amdgcn_s_barrier()
; template <int K, int LD = K>
; __device__ __forceinline__ void gemm_main(const GAS bf16* A, const GAS bf16* Bt, int brow, int bcol, f32x4 (&acc)[2][2][4][2]) {
;     ...
;   const int wid = tid_ >> 6, lane = tid_ & 63, wr = wid >> 2, wc = wid & 3, fr = lane & 15, fq = lane >> 4;
; #pragma unroll
;   for (int a = 0; a < 2; ++a)
; #pragma unroll
;     for (int b = 0; b < 2; ++b)
; #pragma unroll
;       for (int m = 0; m < 4; ++m)
; #pragma unroll
;         for (int n = 0; n < 2; ++n) acc[a][b][m][n] = f32x4{0.f, 0.f, 0.f, 0.f};
;   bf16x8 At[4][2], B0[2][2], B1[2][2];
;   unsigned so0, so1;
;   { int r_, c_; stage_rc(tid_ * 16, r_, c_); so0 = (unsigned)(r_ * LD + c_) * 2u; stage_rc(tid_ * 16 + 8192, r_, c_); so1 = (unsigned)(r_ * LD + c_) * 2u; }
;   const GAS char* pA0 = (const GAS char*)A + (long)brow * LD * 2; const GAS char* pA1 = pA0 + (long)HALF * LD * 2;
;   const GAS char* pB0 = (const GAS char*)Bt + (long)bcol * LD * 2; const GAS char* pB1 = pB0 + (long)HALF * LD * 2;
;   asm volatile("" : "+s"(pA0), "+s"(pA1), "+s"(pB0), "+s"(pB1));
;   constexpr int nt = K / BK;
;   static_assert(K % 128 == 0 && K >= 256, "K");
;   if (wr == 1) BAR;
;   WAIT_V(0); BAR;
;   BAR;
.LBB0_345:
	s_or_b64 exec, exec, s[38:39]
	v_bfe_i32 v7, v134, 27, 1
	v_lshlrev_b32_e32 v5, 4, v134
	v_lshrrev_b32_e32 v7, 22, v7
	v_add_u32_e32 v7, v5, v7
	v_and_b32_e32 v7, 0xfffffc00, v7
	v_sub_u32_e32 v7, v5, v7
	v_lshrrev_b32_e32 v8, 4, v7
	v_bitop3_b32 v8, v8, v7, 32 bitop3:0x6c
	v_ashrrev_i32_e32 v7, 31, v7
	v_ashrrev_i32_e32 v6, 31, v134
	v_lshrrev_b32_e32 v7, 26, v7
	v_lshrrev_b32_e32 v6, 26, v6
	v_add_u32_e32 v7, v8, v7
	v_add_u32_e32 v6, v134, v6
	v_ashrrev_i32_e32 v7, 6, v7
	v_ashrrev_i32_e32 v6, 6, v6
	v_mul_i32_i24_e32 v10, 64, v7
	v_lshlrev_b32_e32 v9, 3, v6
	v_lshlrev_b32_e32 v6, 5, v6
	v_sub_u32_e32 v8, v8, v10
	v_and_b32_e32 v9, 0x1ffff0, v9
	v_and_b32_e32 v6, 32, v6
	v_ashrrev_i16_sdwa v8, v144, sext(v8) dst_sel:DWORD dst_unused:UNUSED_PAD src0_sel:DWORD src1_sel:BYTE_0
	v_add_u32_sdwa v6, v6, sext(v8) dst_sel:DWORD dst_unused:UNUSED_PAD src0_sel:DWORD src1_sel:WORD_0
	v_add_lshl_u32 v7, v7, v9, 11
	v_lshl_add_u32 v130, v6, 1, v7
	v_add_u32_e32 v6, 0x2000, v5
	v_ashrrev_i32_e32 v7, 31, v6
	v_lshrrev_b32_e32 v7, 22, v7
	v_add_u32_e32 v7, v6, v7
	v_ashrrev_i32_e32 v7, 10, v7
	v_mul_i32_i24_e32 v8, 0x400, v7
	v_sub_u32_e32 v6, v6, v8
	v_lshrrev_b32_e32 v8, 4, v6
	v_bitop3_b32 v6, v8, v6, 32 bitop3:0x6c
	v_ashrrev_i32_e32 v9, 31, v6
	v_lshrrev_b32_e32 v9, 26, v9
	v_add_u32_e32 v9, v6, v9
	v_lshrrev_b32_e32 v10, 6, v9
	v_and_b32_e32 v9, 0xc0, v9
	v_lshlrev_b32_e32 v8, 3, v7
	v_lshlrev_b32_e32 v7, 5, v7
	v_sub_u32_e32 v6, v6, v9
	v_and_b32_e32 v8, 0x1ffff0, v8
	v_and_b32_e32 v7, 32, v7
	v_ashrrev_i16_sdwa v6, v144, sext(v6) dst_sel:DWORD dst_unused:UNUSED_PAD src0_sel:DWORD src1_sel:BYTE_0
	v_add_u32_sdwa v6, v7, sext(v6) dst_sel:DWORD dst_unused:UNUSED_PAD src0_sel:DWORD src1_sel:WORD_0
	v_add_lshl_u32 v7, v10, v8, 11
	v_and_b32_e32 v3, 15, v134
	v_lshl_add_u32 v132, v6, 1, v7
	v_lshlrev_b32_e32 v6, 2, v134
	v_and_b32_e32 v4, 48, v134
	v_lshlrev_b32_e32 v3, 6, v3
	v_and_b32_e32 v6, 32, v6
	v_lshlrev_b32_e32 v11, 6, v134
	v_bitop3_b32 v3, v3, v6, v4 bitop3:0x36
	v_lshlrev_b32_e32 v13, 13, v2
	v_and_or_b32 v2, v11, s51, v4
	v_add_u32_e32 v7, s42, v3
	v_add_u32_e32 v8, s43, v3
	v_add_u32_e32 v9, s46, v3
	v_add_u32_e32 v10, s47, v3
	v_and_b32_e32 v12, 0x3000, v11
	v_add_u32_e32 v3, 0x100, v3
	v_xad_u32 v4, v2, v6, s48
	v_or_b32_e32 v6, 0x800, v13
	v_or_b32_e32 v11, 0x1000, v13
	v_or_b32_e32 v14, 0x1800, v13
	v_mov_b32_e32 v2, 0
	v_add_u32_e32 v147, 0x100, v5
	v_add_u32_e32 v153, s42, v5
	v_add_u32_e32 v155, s43, v5
	v_add_u32_e32 v157, s46, v5
	v_add_u32_e32 v159, s47, v5
	v_mov_b32_e32 v133, v131
	s_mov_b32 s5, -2
	v_add_u32_e32 v146, v7, v12
	v_add_u32_e32 v138, v3, v13
	v_add_u32_e32 v137, v4, v6
	v_add_u32_e32 v136, v4, v11
	v_add_u32_e32 v135, v4, v14
	v_add_u32_e32 v143, 0xc000, v147
	v_add_u32_e32 v142, 0xe000, v147
	v_add_u32_e32 v141, v8, v12
	v_add_u32_e32 v148, 0x2000, v147
	v_add_u32_e32 v140, v9, v12
	v_add_u32_e32 v149, 0x4000, v147
	v_add_u32_e32 v150, 0x6000, v147
	v_add_u32_e32 v139, v10, v12
	v_add_u32_e32 v151, 0x8000, v147
	v_add_u32_e32 v152, 0xa000, v147
	v_add_u32_e32 v154, 0x2000, v153
	v_add_u32_e32 v156, 0x2000, v155
	v_add_u32_e32 v158, 0x2000, v157
	v_add_u32_e32 v160, 0x2000, v159
	v_mov_b32_e32 v3, v2
	v_mov_b32_e32 v4, v2
	v_mov_b32_e32 v5, v2
	v_mov_b32_e32 v6, v2
	v_mov_b32_e32 v7, v2
	v_mov_b32_e32 v8, v2
	v_mov_b32_e32 v9, v2
	v_mov_b32_e32 v10, v2
	v_mov_b32_e32 v11, v2
	v_mov_b32_e32 v12, v2
	v_mov_b32_e32 v13, v2
	v_mov_b32_e32 v14, v2
	v_mov_b32_e32 v15, v2
	v_mov_b32_e32 v16, v2
	v_mov_b32_e32 v17, v2
	v_mov_b32_e32 v18, v2
	v_mov_b32_e32 v19, v2
	v_mov_b32_e32 v20, v2
	v_mov_b32_e32 v21, v2
	v_mov_b32_e32 v22, v2
	v_mov_b32_e32 v23, v2
	v_mov_b32_e32 v24, v2
	v_mov_b32_e32 v25, v2
	v_mov_b32_e32 v26, v2
	v_mov_b32_e32 v27, v2
	v_mov_b32_e32 v28, v2
	v_mov_b32_e32 v29, v2
	v_mov_b32_e32 v30, v2
	v_mov_b32_e32 v31, v2
	v_mov_b32_e32 v32, v2
	v_mov_b32_e32 v33, v2
	v_mov_b32_e32 v34, v2
	v_mov_b32_e32 v35, v2
	v_mov_b32_e32 v36, v2
	v_mov_b32_e32 v37, v2
	v_mov_b32_e32 v38, v2
	v_mov_b32_e32 v39, v2
	v_mov_b32_e32 v40, v2
	v_mov_b32_e32 v41, v2
	v_mov_b32_e32 v42, v2
	v_mov_b32_e32 v43, v2
	v_mov_b32_e32 v44, v2
	v_mov_b32_e32 v45, v2
	v_mov_b32_e32 v46, v2
	v_mov_b32_e32 v47, v2
	v_mov_b32_e32 v48, v2
	v_mov_b32_e32 v49, v2
	v_mov_b32_e32 v50, v2
	v_mov_b32_e32 v51, v2
	v_mov_b32_e32 v52, v2
	v_mov_b32_e32 v53, v2
	v_mov_b32_e32 v54, v2
	v_mov_b32_e32 v55, v2
	v_mov_b32_e32 v56, v2
	v_mov_b32_e32 v57, v2
	v_mov_b32_e32 v58, v2
	v_mov_b32_e32 v59, v2
	v_mov_b32_e32 v60, v2
	v_mov_b32_e32 v61, v2
	v_mov_b32_e32 v62, v2
	v_mov_b32_e32 v63, v2
	v_mov_b32_e32 v64, v2
	v_mov_b32_e32 v65, v2
	v_mov_b32_e32 v66, v2
	v_mov_b32_e32 v67, v2
	v_mov_b32_e32 v68, v2
	v_mov_b32_e32 v69, v2
	v_mov_b32_e32 v70, v2
	v_mov_b32_e32 v71, v2
	v_mov_b32_e32 v72, v2
	v_mov_b32_e32 v73, v2
	v_mov_b32_e32 v74, v2
	v_mov_b32_e32 v75, v2
	v_mov_b32_e32 v76, v2
	v_mov_b32_e32 v77, v2
	v_mov_b32_e32 v78, v2
	v_mov_b32_e32 v79, v2
	v_mov_b32_e32 v80, v2
	v_mov_b32_e32 v81, v2
	v_mov_b32_e32 v82, v2
	v_mov_b32_e32 v83, v2
	v_mov_b32_e32 v84, v2
	v_mov_b32_e32 v85, v2
	v_mov_b32_e32 v86, v2
	v_mov_b32_e32 v87, v2
	v_mov_b32_e32 v88, v2
	v_mov_b32_e32 v89, v2
	v_mov_b32_e32 v90, v2
	v_mov_b32_e32 v91, v2
	v_mov_b32_e32 v92, v2
	v_mov_b32_e32 v93, v2
	v_mov_b32_e32 v94, v2
	v_mov_b32_e32 v95, v2
	v_mov_b32_e32 v96, v2
	v_mov_b32_e32 v97, v2
	v_mov_b32_e32 v98, v2
	v_mov_b32_e32 v99, v2
	v_mov_b32_e32 v100, v2
	v_mov_b32_e32 v101, v2
	v_mov_b32_e32 v102, v2
	v_mov_b32_e32 v103, v2
	v_mov_b32_e32 v104, v2
	v_mov_b32_e32 v105, v2
	v_mov_b32_e32 v106, v2
	v_mov_b32_e32 v107, v2
	v_mov_b32_e32 v108, v2
	v_mov_b32_e32 v109, v2
	v_mov_b32_e32 v110, v2
	v_mov_b32_e32 v111, v2
	v_mov_b32_e32 v112, v2
	v_mov_b32_e32 v113, v2
	v_mov_b32_e32 v114, v2
	v_mov_b32_e32 v115, v2
	v_mov_b32_e32 v116, v2
	v_mov_b32_e32 v117, v2
	v_mov_b32_e32 v118, v2
	v_mov_b32_e32 v119, v2
	v_mov_b32_e32 v120, v2
	v_mov_b32_e32 v121, v2
	v_mov_b32_e32 v122, v2
	v_mov_b32_e32 v123, v2
	v_mov_b32_e32 v124, v2
	v_mov_b32_e32 v125, v2
	v_mov_b32_e32 v126, v2
	v_mov_b32_e32 v127, v2
	v_mov_b32_e32 v128, v2
	v_mov_b32_e32 v129, v2
	s_waitcnt vmcnt(0)
	s_barrier
	s_barrier
	.p2align 6

; #define GAS __attribute__((address_space(1)))
; #define WAIT_V(n) asm volatile("s_waitcnt vmcnt(" #n ")" ::: "memory")
; #define BAR __builtin_amdgcn_s_barrier()
; template <int K, int LD = K>
; __device__ __forceinline__ void gemm_main(const GAS bf16* A, const GAS bf16* Bt, int brow, int bcol, f32x4 (&acc)[2][2][4][2]) {
;     ...
;   const int wid = tid_ >> 6, lane = tid_ & 63, wr = wid >> 2, wc = wid & 3, fr = lane & 15, fq = lane >> 4;
; #pragma unroll
;   for (int a = 0; a < 2; ++a)
; #pragma unroll
;     for (int b = 0; b < 2; ++b)
; #pragma unroll
;       for (int m = 0; m < 4; ++m)
; #pragma unroll
;         for (int n = 0; n < 2; ++n) acc[a][b][m][n] = f32x4{0.f, 0.f, 0.f, 0.f};
;   bf16x8 At[4][2], B0[2][2], B1[2][2];
;   unsigned so0, so1;
;   { int r_, c_; stage_rc(tid_ * 16, r_, c_); so0 = (unsigned)(r_ * LD + c_) * 2u; stage_rc(tid_ * 16 + 8192, r_, c_); so1 = (unsigned)(r_ * LD + c_) * 2u; }
;   const GAS char* pA0 = (const GAS char*)A + (long)brow * LD * 2; const GAS char* pA1 = pA0 + (long)HALF * LD * 2;
;   const GAS char* pB0 = (const GAS char*)Bt + (long)bcol * LD * 2; const GAS char* pB1 = pB0 + (long)HALF * LD * 2;
;   asm volatile("" : "+s"(pA0), "+s"(pA1), "+s"(pB0), "+s"(pB1));
;   constexpr int nt = K / BK;
;   static_assert(K % 128 == 0 && K >= 256, "K");
;   if (wr == 1) BAR;
;   WAIT_V(0); BAR;
;   BAR;
.LBB0_708:
	s_or_b64 exec, exec, s[30:31]
	v_bfe_i32 v6, v134, 27, 1
	v_lshlrev_b32_e32 v141, 4, v134
	v_lshrrev_b32_e32 v6, 22, v6
	v_add_u32_e32 v6, v141, v6
	v_and_b32_e32 v6, 0xfffffc00, v6
	v_sub_u32_e32 v6, v141, v6
	v_lshrrev_b32_e32 v7, 4, v6
	v_bitop3_b32 v7, v7, v6, 32 bitop3:0x6c
	v_ashrrev_i32_e32 v6, 31, v6
	v_ashrrev_i32_e32 v5, 31, v134
	v_lshrrev_b32_e32 v6, 26, v6
	v_lshrrev_b32_e32 v5, 26, v5
	v_add_u32_e32 v6, v7, v6
	v_add_u32_e32 v5, v134, v5
	v_ashrrev_i32_e32 v6, 6, v6
	v_ashrrev_i32_e32 v5, 6, v5
	v_mul_i32_i24_e32 v9, 64, v6
	v_lshlrev_b32_e32 v8, 3, v5
	v_lshlrev_b32_e32 v5, 5, v5
	v_sub_u32_e32 v7, v7, v9
	v_and_b32_e32 v8, 0x3ffff0, v8
	v_and_b32_e32 v5, 32, v5
	v_ashrrev_i16_sdwa v7, v1, sext(v7) dst_sel:DWORD dst_unused:UNUSED_PAD src0_sel:DWORD src1_sel:BYTE_0
	v_add_u32_sdwa v5, v5, sext(v7) dst_sel:DWORD dst_unused:UNUSED_PAD src0_sel:DWORD src1_sel:WORD_0
	v_add_lshl_u32 v6, v6, v8, 10
	v_lshl_add_u32 v130, v5, 1, v6
	v_add_u32_e32 v5, 0x2000, v141
	v_ashrrev_i32_e32 v6, 31, v5
	v_lshrrev_b32_e32 v6, 22, v6
	v_add_u32_e32 v6, v5, v6
	v_ashrrev_i32_e32 v6, 10, v6
	v_mul_i32_i24_e32 v7, 0x400, v6
	v_sub_u32_e32 v5, v5, v7
	v_lshrrev_b32_e32 v7, 4, v5
	v_bitop3_b32 v5, v7, v5, 32 bitop3:0x6c
	v_ashrrev_i32_e32 v8, 31, v5
	v_lshrrev_b32_e32 v8, 26, v8
	v_add_u32_e32 v8, v5, v8
	v_lshrrev_b32_e32 v9, 6, v8
	v_and_b32_e32 v8, 0xc0, v8
	v_lshlrev_b32_e32 v7, 3, v6
	v_lshlrev_b32_e32 v6, 5, v6
	v_sub_u32_e32 v5, v5, v8
	v_and_b32_e32 v7, 0x3ffff0, v7
	v_and_b32_e32 v6, 32, v6
	v_ashrrev_i16_sdwa v5, v1, sext(v5) dst_sel:DWORD dst_unused:UNUSED_PAD src0_sel:DWORD src1_sel:BYTE_0
	v_add_u32_sdwa v5, v6, sext(v5) dst_sel:DWORD dst_unused:UNUSED_PAD src0_sel:DWORD src1_sel:WORD_0
	v_add_lshl_u32 v6, v9, v7, 10
	v_and_b32_e32 v3, 15, v134
	v_lshl_add_u32 v132, v5, 1, v6
	v_lshlrev_b32_e32 v5, 2, v134
	v_and_b32_e32 v4, 48, v134
	v_lshlrev_b32_e32 v3, 6, v3
	v_and_b32_e32 v5, 32, v5
	v_lshlrev_b32_e32 v10, 6, v134
	v_bitop3_b32 v3, v3, v5, v4 bitop3:0x36
	v_lshlrev_b32_e32 v12, 13, v2
	v_and_or_b32 v2, v10, s54, v4
	v_add_u32_e32 v6, s47, v3
	v_add_u32_e32 v7, s48, v3
	v_add_u32_e32 v8, s49, v3
	v_add_u32_e32 v9, s50, v3
	v_and_b32_e32 v11, 0x3000, v10
	v_add_u32_e32 v3, 0x100, v3
	v_xad_u32 v4, v2, v5, s51
	v_or_b32_e32 v5, 0x800, v12
	v_or_b32_e32 v10, 0x1000, v12
	v_or_b32_e32 v13, 0x1800, v12
	v_mov_b32_e32 v2, 0
	v_mov_b32_e32 v133, v131
	s_mov_b32 s17, -2
	v_add_u32_e32 v143, v6, v11
	v_add_u32_e32 v138, v3, v12
	v_add_u32_e32 v137, v4, v5
	v_add_u32_e32 v136, v4, v10
	v_add_u32_e32 v135, v4, v13
	v_add_u32_e32 v142, v7, v11
	v_add_u32_e32 v140, v8, v11
	v_add_u32_e32 v139, v9, v11
	v_mov_b32_e32 v3, v2
	v_mov_b32_e32 v4, v2
	v_mov_b32_e32 v5, v2
	v_mov_b32_e32 v6, v2
	v_mov_b32_e32 v7, v2
	v_mov_b32_e32 v8, v2
	v_mov_b32_e32 v9, v2
	v_mov_b32_e32 v10, v2
	v_mov_b32_e32 v11, v2
	v_mov_b32_e32 v12, v2
	v_mov_b32_e32 v13, v2
	v_mov_b32_e32 v14, v2
	v_mov_b32_e32 v15, v2
	v_mov_b32_e32 v16, v2
	v_mov_b32_e32 v17, v2
	v_mov_b32_e32 v18, v2
	v_mov_b32_e32 v19, v2
	v_mov_b32_e32 v20, v2
	v_mov_b32_e32 v21, v2
	v_mov_b32_e32 v22, v2
	v_mov_b32_e32 v23, v2
	v_mov_b32_e32 v24, v2
	v_mov_b32_e32 v25, v2
	v_mov_b32_e32 v26, v2
	v_mov_b32_e32 v27, v2
	v_mov_b32_e32 v28, v2
	v_mov_b32_e32 v29, v2
	v_mov_b32_e32 v30, v2
	v_mov_b32_e32 v31, v2
	v_mov_b32_e32 v32, v2
	v_mov_b32_e32 v33, v2
	v_mov_b32_e32 v34, v2
	v_mov_b32_e32 v35, v2
	v_mov_b32_e32 v36, v2
	v_mov_b32_e32 v37, v2
	v_mov_b32_e32 v38, v2
	v_mov_b32_e32 v39, v2
	v_mov_b32_e32 v40, v2
	v_mov_b32_e32 v41, v2
	v_mov_b32_e32 v42, v2
	v_mov_b32_e32 v43, v2
	v_mov_b32_e32 v44, v2
	v_mov_b32_e32 v45, v2
	v_mov_b32_e32 v46, v2
	v_mov_b32_e32 v47, v2
	v_mov_b32_e32 v48, v2
	v_mov_b32_e32 v49, v2
	v_mov_b32_e32 v50, v2
	v_mov_b32_e32 v51, v2
	v_mov_b32_e32 v52, v2
	v_mov_b32_e32 v53, v2
	v_mov_b32_e32 v54, v2
	v_mov_b32_e32 v55, v2
	v_mov_b32_e32 v56, v2
	v_mov_b32_e32 v57, v2
	v_mov_b32_e32 v58, v2
	v_mov_b32_e32 v59, v2
	v_mov_b32_e32 v60, v2
	v_mov_b32_e32 v61, v2
	v_mov_b32_e32 v62, v2
	v_mov_b32_e32 v63, v2
	v_mov_b32_e32 v64, v2
	v_mov_b32_e32 v65, v2
	v_mov_b32_e32 v66, v2
	v_mov_b32_e32 v67, v2
	v_mov_b32_e32 v68, v2
	v_mov_b32_e32 v69, v2
	v_mov_b32_e32 v70, v2
	v_mov_b32_e32 v71, v2
	v_mov_b32_e32 v72, v2
	v_mov_b32_e32 v73, v2
	v_mov_b32_e32 v74, v2
	v_mov_b32_e32 v75, v2
	v_mov_b32_e32 v76, v2
	v_mov_b32_e32 v77, v2
	v_mov_b32_e32 v78, v2
	v_mov_b32_e32 v79, v2
	v_mov_b32_e32 v80, v2
	v_mov_b32_e32 v81, v2
	v_mov_b32_e32 v82, v2
	v_mov_b32_e32 v83, v2
	v_mov_b32_e32 v84, v2
	v_mov_b32_e32 v85, v2
	v_mov_b32_e32 v86, v2
	v_mov_b32_e32 v87, v2
	v_mov_b32_e32 v88, v2
	v_mov_b32_e32 v89, v2
	v_mov_b32_e32 v90, v2
	v_mov_b32_e32 v91, v2
	v_mov_b32_e32 v92, v2
	v_mov_b32_e32 v93, v2
	v_mov_b32_e32 v94, v2
	v_mov_b32_e32 v95, v2
	v_mov_b32_e32 v96, v2
	v_mov_b32_e32 v97, v2
	v_mov_b32_e32 v98, v2
	v_mov_b32_e32 v99, v2
	v_mov_b32_e32 v100, v2
	v_mov_b32_e32 v101, v2
	v_mov_b32_e32 v102, v2
	v_mov_b32_e32 v103, v2
	v_mov_b32_e32 v104, v2
	v_mov_b32_e32 v105, v2
	v_mov_b32_e32 v106, v2
	v_mov_b32_e32 v107, v2
	v_mov_b32_e32 v108, v2
	v_mov_b32_e32 v109, v2
	v_mov_b32_e32 v110, v2
	v_mov_b32_e32 v111, v2
	v_mov_b32_e32 v112, v2
	v_mov_b32_e32 v113, v2
	v_mov_b32_e32 v114, v2
	v_mov_b32_e32 v115, v2
	v_mov_b32_e32 v116, v2
	v_mov_b32_e32 v117, v2
	v_mov_b32_e32 v118, v2
	v_mov_b32_e32 v119, v2
	v_mov_b32_e32 v120, v2
	v_mov_b32_e32 v121, v2
	v_mov_b32_e32 v122, v2
	v_mov_b32_e32 v123, v2
	v_mov_b32_e32 v124, v2
	v_mov_b32_e32 v125, v2
	v_mov_b32_e32 v126, v2
	v_mov_b32_e32 v127, v2
	v_mov_b32_e32 v128, v2
	v_mov_b32_e32 v129, v2
	s_waitcnt vmcnt(0)
	s_barrier
	s_barrier
	.p2align 6

; #define GAS __attribute__((address_space(1)))
; #define WAIT_V(n) asm volatile("s_waitcnt vmcnt(" #n ")" ::: "memory")
; #define BAR __builtin_amdgcn_s_barrier()
; template <int K, int LD = K>
; __device__ __forceinline__ void gemm_main(const GAS bf16* A, const GAS bf16* Bt, int brow, int bcol, f32x4 (&acc)[2][2][4][2]) {
;     ...
;   const int wid = tid_ >> 6, lane = tid_ & 63, wr = wid >> 2, wc = wid & 3, fr = lane & 15, fq = lane >> 4;
; #pragma unroll
;   for (int a = 0; a < 2; ++a)
; #pragma unroll
;     for (int b = 0; b < 2; ++b)
; #pragma unroll
;       for (int m = 0; m < 4; ++m)
; #pragma unroll
;         for (int n = 0; n < 2; ++n) acc[a][b][m][n] = f32x4{0.f, 0.f, 0.f, 0.f};
;   bf16x8 At[4][2], B0[2][2], B1[2][2];
;   unsigned so0, so1;
;   { int r_, c_; stage_rc(tid_ * 16, r_, c_); so0 = (unsigned)(r_ * LD + c_) * 2u; stage_rc(tid_ * 16 + 8192, r_, c_); so1 = (unsigned)(r_ * LD + c_) * 2u; }
;   const GAS char* pA0 = (const GAS char*)A + (long)brow * LD * 2; const GAS char* pA1 = pA0 + (long)HALF * LD * 2;
;   const GAS char* pB0 = (const GAS char*)Bt + (long)bcol * LD * 2; const GAS char* pB1 = pB0 + (long)HALF * LD * 2;
;   asm volatile("" : "+s"(pA0), "+s"(pA1), "+s"(pB0), "+s"(pB1));
;   constexpr int nt = K / BK;
;   static_assert(K % 128 == 0 && K >= 256, "K");
;   if (wr == 1) BAR;
;   WAIT_V(0); BAR;
;   BAR;
.LBB0_714:
	s_or_b64 exec, exec, s[28:29]
	v_bfe_i32 v6, v134, 27, 1
	v_lshlrev_b32_e32 v141, 4, v134
	v_lshrrev_b32_e32 v6, 22, v6
	v_add_u32_e32 v6, v141, v6
	v_and_b32_e32 v6, 0xfffffc00, v6
	v_sub_u32_e32 v6, v141, v6
	v_lshrrev_b32_e32 v7, 4, v6
	v_bitop3_b32 v7, v7, v6, 32 bitop3:0x6c
	v_ashrrev_i32_e32 v6, 31, v6
	v_ashrrev_i32_e32 v5, 31, v134
	v_lshrrev_b32_e32 v6, 26, v6
	v_lshrrev_b32_e32 v5, 26, v5
	v_add_u32_e32 v6, v7, v6
	v_add_u32_e32 v5, v134, v5
	v_ashrrev_i32_e32 v6, 6, v6
	v_ashrrev_i32_e32 v5, 6, v5
	v_mul_i32_i24_e32 v9, 64, v6
	v_lshlrev_b32_e32 v8, 3, v5
	v_lshlrev_b32_e32 v5, 5, v5
	v_sub_u32_e32 v7, v7, v9
	v_and_b32_e32 v8, 0x3ffff0, v8
	v_and_b32_e32 v5, 32, v5
	v_ashrrev_i16_sdwa v7, v1, sext(v7) dst_sel:DWORD dst_unused:UNUSED_PAD src0_sel:DWORD src1_sel:BYTE_0
	v_add_u32_sdwa v5, v5, sext(v7) dst_sel:DWORD dst_unused:UNUSED_PAD src0_sel:DWORD src1_sel:WORD_0
	v_add_lshl_u32 v6, v6, v8, 10
	v_lshl_add_u32 v130, v5, 1, v6
	v_add_u32_e32 v5, 0x2000, v141
	v_ashrrev_i32_e32 v6, 31, v5
	v_lshrrev_b32_e32 v6, 22, v6
	v_add_u32_e32 v6, v5, v6
	v_ashrrev_i32_e32 v6, 10, v6
	v_mul_i32_i24_e32 v7, 0x400, v6
	v_sub_u32_e32 v5, v5, v7
	v_lshrrev_b32_e32 v7, 4, v5
	v_bitop3_b32 v5, v7, v5, 32 bitop3:0x6c
	v_ashrrev_i32_e32 v8, 31, v5
	v_lshrrev_b32_e32 v8, 26, v8
	v_add_u32_e32 v8, v5, v8
	v_lshrrev_b32_e32 v9, 6, v8
	v_and_b32_e32 v8, 0xc0, v8
	v_lshlrev_b32_e32 v7, 3, v6
	v_lshlrev_b32_e32 v6, 5, v6
	v_sub_u32_e32 v5, v5, v8
	v_and_b32_e32 v7, 0x3ffff0, v7
	v_and_b32_e32 v6, 32, v6
	v_ashrrev_i16_sdwa v5, v1, sext(v5) dst_sel:DWORD dst_unused:UNUSED_PAD src0_sel:DWORD src1_sel:BYTE_0
	v_add_u32_sdwa v5, v6, sext(v5) dst_sel:DWORD dst_unused:UNUSED_PAD src0_sel:DWORD src1_sel:WORD_0
	v_add_lshl_u32 v6, v9, v7, 10
	v_and_b32_e32 v3, 15, v134
	v_lshl_add_u32 v132, v5, 1, v6
	v_lshlrev_b32_e32 v5, 2, v134
	v_and_b32_e32 v4, 48, v134
	v_lshlrev_b32_e32 v3, 6, v3
	v_and_b32_e32 v5, 32, v5
	v_lshlrev_b32_e32 v10, 6, v134
	v_bitop3_b32 v3, v3, v5, v4 bitop3:0x36
	v_lshlrev_b32_e32 v12, 13, v2
	v_and_or_b32 v2, v10, s54, v4
	v_add_u32_e32 v6, s47, v3
	v_add_u32_e32 v7, s48, v3
	v_add_u32_e32 v8, s49, v3
	v_add_u32_e32 v9, s50, v3
	v_and_b32_e32 v11, 0x3000, v10
	v_add_u32_e32 v3, 0x100, v3
	v_xad_u32 v4, v2, v5, s51
	v_or_b32_e32 v5, 0x800, v12
	v_or_b32_e32 v10, 0x1000, v12
	v_or_b32_e32 v13, 0x1800, v12
	v_mov_b32_e32 v2, 0
	v_mov_b32_e32 v133, v131
	s_mov_b32 s17, -2
	v_add_u32_e32 v143, v6, v11
	v_add_u32_e32 v138, v3, v12
	v_add_u32_e32 v137, v4, v5
	v_add_u32_e32 v136, v4, v10
	v_add_u32_e32 v135, v4, v13
	v_add_u32_e32 v142, v7, v11
	v_add_u32_e32 v140, v8, v11
	v_add_u32_e32 v139, v9, v11
	v_mov_b32_e32 v3, v2
	v_mov_b32_e32 v4, v2
	v_mov_b32_e32 v5, v2
	v_mov_b32_e32 v6, v2
	v_mov_b32_e32 v7, v2
	v_mov_b32_e32 v8, v2
	v_mov_b32_e32 v9, v2
	v_mov_b32_e32 v10, v2
	v_mov_b32_e32 v11, v2
	v_mov_b32_e32 v12, v2
	v_mov_b32_e32 v13, v2
	v_mov_b32_e32 v14, v2
	v_mov_b32_e32 v15, v2
	v_mov_b32_e32 v16, v2
	v_mov_b32_e32 v17, v2
	v_mov_b32_e32 v18, v2
	v_mov_b32_e32 v19, v2
	v_mov_b32_e32 v20, v2
	v_mov_b32_e32 v21, v2
	v_mov_b32_e32 v22, v2
	v_mov_b32_e32 v23, v2
	v_mov_b32_e32 v24, v2
	v_mov_b32_e32 v25, v2
	v_mov_b32_e32 v26, v2
	v_mov_b32_e32 v27, v2
	v_mov_b32_e32 v28, v2
	v_mov_b32_e32 v29, v2
	v_mov_b32_e32 v30, v2
	v_mov_b32_e32 v31, v2
	v_mov_b32_e32 v32, v2
	v_mov_b32_e32 v33, v2
	v_mov_b32_e32 v34, v2
	v_mov_b32_e32 v35, v2
	v_mov_b32_e32 v36, v2
	v_mov_b32_e32 v37, v2
	v_mov_b32_e32 v38, v2
	v_mov_b32_e32 v39, v2
	v_mov_b32_e32 v40, v2
	v_mov_b32_e32 v41, v2
	v_mov_b32_e32 v42, v2
	v_mov_b32_e32 v43, v2
	v_mov_b32_e32 v44, v2
	v_mov_b32_e32 v45, v2
	v_mov_b32_e32 v46, v2
	v_mov_b32_e32 v47, v2
	v_mov_b32_e32 v48, v2
	v_mov_b32_e32 v49, v2
	v_mov_b32_e32 v50, v2
	v_mov_b32_e32 v51, v2
	v_mov_b32_e32 v52, v2
	v_mov_b32_e32 v53, v2
	v_mov_b32_e32 v54, v2
	v_mov_b32_e32 v55, v2
	v_mov_b32_e32 v56, v2
	v_mov_b32_e32 v57, v2
	v_mov_b32_e32 v58, v2
	v_mov_b32_e32 v59, v2
	v_mov_b32_e32 v60, v2
	v_mov_b32_e32 v61, v2
	v_mov_b32_e32 v62, v2
	v_mov_b32_e32 v63, v2
	v_mov_b32_e32 v64, v2
	v_mov_b32_e32 v65, v2
	v_mov_b32_e32 v66, v2
	v_mov_b32_e32 v67, v2
	v_mov_b32_e32 v68, v2
	v_mov_b32_e32 v69, v2
	v_mov_b32_e32 v70, v2
	v_mov_b32_e32 v71, v2
	v_mov_b32_e32 v72, v2
	v_mov_b32_e32 v73, v2
	v_mov_b32_e32 v74, v2
	v_mov_b32_e32 v75, v2
	v_mov_b32_e32 v76, v2
	v_mov_b32_e32 v77, v2
	v_mov_b32_e32 v78, v2
	v_mov_b32_e32 v79, v2
	v_mov_b32_e32 v80, v2
	v_mov_b32_e32 v81, v2
	v_mov_b32_e32 v82, v2
	v_mov_b32_e32 v83, v2
	v_mov_b32_e32 v84, v2
	v_mov_b32_e32 v85, v2
	v_mov_b32_e32 v86, v2
	v_mov_b32_e32 v87, v2
	v_mov_b32_e32 v88, v2
	v_mov_b32_e32 v89, v2
	v_mov_b32_e32 v90, v2
	v_mov_b32_e32 v91, v2
	v_mov_b32_e32 v92, v2
	v_mov_b32_e32 v93, v2
	v_mov_b32_e32 v94, v2
	v_mov_b32_e32 v95, v2
	v_mov_b32_e32 v96, v2
	v_mov_b32_e32 v97, v2
	v_mov_b32_e32 v98, v2
	v_mov_b32_e32 v99, v2
	v_mov_b32_e32 v100, v2
	v_mov_b32_e32 v101, v2
	v_mov_b32_e32 v102, v2
	v_mov_b32_e32 v103, v2
	v_mov_b32_e32 v104, v2
	v_mov_b32_e32 v105, v2
	v_mov_b32_e32 v106, v2
	v_mov_b32_e32 v107, v2
	v_mov_b32_e32 v108, v2
	v_mov_b32_e32 v109, v2
	v_mov_b32_e32 v110, v2
	v_mov_b32_e32 v111, v2
	v_mov_b32_e32 v112, v2
	v_mov_b32_e32 v113, v2
	v_mov_b32_e32 v114, v2
	v_mov_b32_e32 v115, v2
	v_mov_b32_e32 v116, v2
	v_mov_b32_e32 v117, v2
	v_mov_b32_e32 v118, v2
	v_mov_b32_e32 v119, v2
	v_mov_b32_e32 v120, v2
	v_mov_b32_e32 v121, v2
	v_mov_b32_e32 v122, v2
	v_mov_b32_e32 v123, v2
	v_mov_b32_e32 v124, v2
	v_mov_b32_e32 v125, v2
	v_mov_b32_e32 v126, v2
	v_mov_b32_e32 v127, v2
	v_mov_b32_e32 v128, v2
	v_mov_b32_e32 v129, v2
	s_waitcnt vmcnt(0)
	s_barrier
	s_barrier
	.p2align 6

; #define GAS __attribute__((address_space(1)))
; #define WAIT_V(n) asm volatile("s_waitcnt vmcnt(" #n ")" ::: "memory")
; #define BAR __builtin_amdgcn_s_barrier()
; template <int K, int LD = K>
; __device__ __forceinline__ void gemm_main(const GAS bf16* A, const GAS bf16* Bt, int brow, int bcol, f32x4 (&acc)[2][2][4][2]) {
;     ...
;   const int wid = tid_ >> 6, lane = tid_ & 63, wr = wid >> 2, wc = wid & 3, fr = lane & 15, fq = lane >> 4;
; #pragma unroll
;   for (int a = 0; a < 2; ++a)
; #pragma unroll
;     for (int b = 0; b < 2; ++b)
; #pragma unroll
;       for (int m = 0; m < 4; ++m)
; #pragma unroll
;         for (int n = 0; n < 2; ++n) acc[a][b][m][n] = f32x4{0.f, 0.f, 0.f, 0.f};
;   bf16x8 At[4][2], B0[2][2], B1[2][2];
;   unsigned so0, so1;
;   { int r_, c_; stage_rc(tid_ * 16, r_, c_); so0 = (unsigned)(r_ * LD + c_) * 2u; stage_rc(tid_ * 16 + 8192, r_, c_); so1 = (unsigned)(r_ * LD + c_) * 2u; }
;   const GAS char* pA0 = (const GAS char*)A + (long)brow * LD * 2; const GAS char* pA1 = pA0 + (long)HALF * LD * 2;
;   const GAS char* pB0 = (const GAS char*)Bt + (long)bcol * LD * 2; const GAS char* pB1 = pB0 + (long)HALF * LD * 2;
;   asm volatile("" : "+s"(pA0), "+s"(pA1), "+s"(pB0), "+s"(pB1));
;   constexpr int nt = K / BK;
;   static_assert(K % 128 == 0 && K >= 256, "K");
;   if (wr == 1) BAR;
;   WAIT_V(0); BAR;
;   BAR;
.LBB0_766:
	s_or_b64 exec, exec, s[22:23]
	v_bfe_i32 v7, v134, 27, 1
	v_lshlrev_b32_e32 v5, 4, v134
	v_lshrrev_b32_e32 v7, 22, v7
	v_add_u32_e32 v7, v5, v7
	v_and_b32_e32 v7, 0xfffffc00, v7
	v_sub_u32_e32 v7, v5, v7
	v_lshrrev_b32_e32 v8, 4, v7
	v_bitop3_b32 v8, v8, v7, 32 bitop3:0x6c
	v_ashrrev_i32_e32 v7, 31, v7
	v_ashrrev_i32_e32 v6, 31, v134
	v_lshrrev_b32_e32 v7, 26, v7
	v_lshrrev_b32_e32 v6, 26, v6
	v_add_u32_e32 v7, v8, v7
	v_add_u32_e32 v6, v134, v6
	v_ashrrev_i32_e32 v7, 6, v7
	v_ashrrev_i32_e32 v6, 6, v6
	v_mul_i32_i24_e32 v10, 64, v7
	v_lshlrev_b32_e32 v9, 3, v6
	v_lshlrev_b32_e32 v6, 5, v6
	v_sub_u32_e32 v8, v8, v10
	v_and_b32_e32 v9, 0x1ffff0, v9
	v_and_b32_e32 v6, 32, v6
	v_ashrrev_i16_sdwa v8, v1, sext(v8) dst_sel:DWORD dst_unused:UNUSED_PAD src0_sel:DWORD src1_sel:BYTE_0
	v_add_u32_sdwa v6, v6, sext(v8) dst_sel:DWORD dst_unused:UNUSED_PAD src0_sel:DWORD src1_sel:WORD_0
	v_add_lshl_u32 v7, v7, v9, 11
	v_lshl_add_u32 v130, v6, 1, v7
	v_add_u32_e32 v6, 0x2000, v5
	v_ashrrev_i32_e32 v7, 31, v6
	v_lshrrev_b32_e32 v7, 22, v7
	v_add_u32_e32 v7, v6, v7
	v_ashrrev_i32_e32 v7, 10, v7
	v_mul_i32_i24_e32 v8, 0x400, v7
	v_sub_u32_e32 v6, v6, v8
	v_lshrrev_b32_e32 v8, 4, v6
	v_bitop3_b32 v6, v8, v6, 32 bitop3:0x6c
	v_ashrrev_i32_e32 v9, 31, v6
	v_lshrrev_b32_e32 v9, 26, v9
	v_add_u32_e32 v9, v6, v9
	v_lshrrev_b32_e32 v10, 6, v9
	v_and_b32_e32 v9, 0xc0, v9
	v_lshlrev_b32_e32 v8, 3, v7
	v_lshlrev_b32_e32 v7, 5, v7
	v_sub_u32_e32 v6, v6, v9
	v_and_b32_e32 v8, 0x1ffff0, v8
	v_and_b32_e32 v7, 32, v7
	v_ashrrev_i16_sdwa v6, v1, sext(v6) dst_sel:DWORD dst_unused:UNUSED_PAD src0_sel:DWORD src1_sel:BYTE_0
	v_add_u32_sdwa v6, v7, sext(v6) dst_sel:DWORD dst_unused:UNUSED_PAD src0_sel:DWORD src1_sel:WORD_0
	v_add_lshl_u32 v7, v10, v8, 11
	v_and_b32_e32 v3, 15, v134
	v_lshl_add_u32 v132, v6, 1, v7
	v_lshlrev_b32_e32 v6, 2, v134
	v_and_b32_e32 v4, 48, v134
	v_lshlrev_b32_e32 v3, 6, v3
	v_and_b32_e32 v6, 32, v6
	v_lshlrev_b32_e32 v11, 6, v134
	v_bitop3_b32 v3, v3, v6, v4 bitop3:0x36
	v_lshlrev_b32_e32 v13, 13, v2
	v_and_or_b32 v2, v11, s39, v4
	v_add_u32_e32 v7, s35, v3
	v_add_u32_e32 v8, s36, v3
	v_add_u32_e32 v9, s37, v3
	v_add_u32_e32 v10, s38, v3
	v_and_b32_e32 v12, 0x3000, v11
	v_add_u32_e32 v3, 0x100, v3
	v_xad_u32 v4, v2, v6, s34
	v_or_b32_e32 v6, 0x800, v13
	v_or_b32_e32 v11, 0x1000, v13
	v_or_b32_e32 v14, 0x1800, v13
	v_mov_b32_e32 v2, 0
	v_add_u32_e32 v145, 0x100, v5
	v_add_u32_e32 v151, s35, v5
	v_add_u32_e32 v153, s36, v5
	v_add_u32_e32 v155, s37, v5
	v_add_u32_e32 v157, s38, v5
	v_mov_b32_e32 v133, v131
	s_mov_b32 s15, -2
	v_add_u32_e32 v144, v7, v12
	v_add_u32_e32 v138, v3, v13
	v_add_u32_e32 v137, v4, v6
	v_add_u32_e32 v136, v4, v11
	v_add_u32_e32 v135, v4, v14
	v_add_u32_e32 v143, 0xc000, v145
	v_add_u32_e32 v142, 0xe000, v145
	v_add_u32_e32 v141, v8, v12
	v_add_u32_e32 v146, 0x2000, v145
	v_add_u32_e32 v140, v9, v12
	v_add_u32_e32 v147, 0x4000, v145
	v_add_u32_e32 v148, 0x6000, v145
	v_add_u32_e32 v139, v10, v12
	v_add_u32_e32 v149, 0x8000, v145
	v_add_u32_e32 v150, 0xa000, v145
	v_add_u32_e32 v152, 0x2000, v151
	v_add_u32_e32 v154, 0x2000, v153
	v_add_u32_e32 v156, 0x2000, v155
	v_add_u32_e32 v158, 0x2000, v157
	v_mov_b32_e32 v3, v2
	v_mov_b32_e32 v4, v2
	v_mov_b32_e32 v5, v2
	v_mov_b32_e32 v6, v2
	v_mov_b32_e32 v7, v2
	v_mov_b32_e32 v8, v2
	v_mov_b32_e32 v9, v2
	v_mov_b32_e32 v10, v2
	v_mov_b32_e32 v11, v2
	v_mov_b32_e32 v12, v2
	v_mov_b32_e32 v13, v2
	v_mov_b32_e32 v14, v2
	v_mov_b32_e32 v15, v2
	v_mov_b32_e32 v16, v2
	v_mov_b32_e32 v17, v2
	v_mov_b32_e32 v18, v2
	v_mov_b32_e32 v19, v2
	v_mov_b32_e32 v20, v2
	v_mov_b32_e32 v21, v2
	v_mov_b32_e32 v22, v2
	v_mov_b32_e32 v23, v2
	v_mov_b32_e32 v24, v2
	v_mov_b32_e32 v25, v2
	v_mov_b32_e32 v26, v2
	v_mov_b32_e32 v27, v2
	v_mov_b32_e32 v28, v2
	v_mov_b32_e32 v29, v2
	v_mov_b32_e32 v30, v2
	v_mov_b32_e32 v31, v2
	v_mov_b32_e32 v32, v2
	v_mov_b32_e32 v33, v2
	v_mov_b32_e32 v34, v2
	v_mov_b32_e32 v35, v2
	v_mov_b32_e32 v36, v2
	v_mov_b32_e32 v37, v2
	v_mov_b32_e32 v38, v2
	v_mov_b32_e32 v39, v2
	v_mov_b32_e32 v40, v2
	v_mov_b32_e32 v41, v2
	v_mov_b32_e32 v42, v2
	v_mov_b32_e32 v43, v2
	v_mov_b32_e32 v44, v2
	v_mov_b32_e32 v45, v2
	v_mov_b32_e32 v46, v2
	v_mov_b32_e32 v47, v2
	v_mov_b32_e32 v48, v2
	v_mov_b32_e32 v49, v2
	v_mov_b32_e32 v50, v2
	v_mov_b32_e32 v51, v2
	v_mov_b32_e32 v52, v2
	v_mov_b32_e32 v53, v2
	v_mov_b32_e32 v54, v2
	v_mov_b32_e32 v55, v2
	v_mov_b32_e32 v56, v2
	v_mov_b32_e32 v57, v2
	v_mov_b32_e32 v58, v2
	v_mov_b32_e32 v59, v2
	v_mov_b32_e32 v60, v2
	v_mov_b32_e32 v61, v2
	v_mov_b32_e32 v62, v2
	v_mov_b32_e32 v63, v2
	v_mov_b32_e32 v64, v2
	v_mov_b32_e32 v65, v2
	v_mov_b32_e32 v66, v2
	v_mov_b32_e32 v67, v2
	v_mov_b32_e32 v68, v2
	v_mov_b32_e32 v69, v2
	v_mov_b32_e32 v70, v2
	v_mov_b32_e32 v71, v2
	v_mov_b32_e32 v72, v2
	v_mov_b32_e32 v73, v2
	v_mov_b32_e32 v74, v2
	v_mov_b32_e32 v75, v2
	v_mov_b32_e32 v76, v2
	v_mov_b32_e32 v77, v2
	v_mov_b32_e32 v78, v2
	v_mov_b32_e32 v79, v2
	v_mov_b32_e32 v80, v2
	v_mov_b32_e32 v81, v2
	v_mov_b32_e32 v82, v2
	v_mov_b32_e32 v83, v2
	v_mov_b32_e32 v84, v2
	v_mov_b32_e32 v85, v2
	v_mov_b32_e32 v86, v2
	v_mov_b32_e32 v87, v2
	v_mov_b32_e32 v88, v2
	v_mov_b32_e32 v89, v2
	v_mov_b32_e32 v90, v2
	v_mov_b32_e32 v91, v2
	v_mov_b32_e32 v92, v2
	v_mov_b32_e32 v93, v2
	v_mov_b32_e32 v94, v2
	v_mov_b32_e32 v95, v2
	v_mov_b32_e32 v96, v2
	v_mov_b32_e32 v97, v2
	v_mov_b32_e32 v98, v2
	v_mov_b32_e32 v99, v2
	v_mov_b32_e32 v100, v2
	v_mov_b32_e32 v101, v2
	v_mov_b32_e32 v102, v2
	v_mov_b32_e32 v103, v2
	v_mov_b32_e32 v104, v2
	v_mov_b32_e32 v105, v2
	v_mov_b32_e32 v106, v2
	v_mov_b32_e32 v107, v2
	v_mov_b32_e32 v108, v2
	v_mov_b32_e32 v109, v2
	v_mov_b32_e32 v110, v2
	v_mov_b32_e32 v111, v2
	v_mov_b32_e32 v112, v2
	v_mov_b32_e32 v113, v2
	v_mov_b32_e32 v114, v2
	v_mov_b32_e32 v115, v2
	v_mov_b32_e32 v116, v2
	v_mov_b32_e32 v117, v2
	v_mov_b32_e32 v118, v2
	v_mov_b32_e32 v119, v2
	v_mov_b32_e32 v120, v2
	v_mov_b32_e32 v121, v2
	v_mov_b32_e32 v122, v2
	v_mov_b32_e32 v123, v2
	v_mov_b32_e32 v124, v2
	v_mov_b32_e32 v125, v2
	v_mov_b32_e32 v126, v2
	v_mov_b32_e32 v127, v2
	v_mov_b32_e32 v128, v2
	v_mov_b32_e32 v129, v2
	s_waitcnt vmcnt(0)
	s_barrier
	s_barrier
	.p2align 6

; #define GAS __attribute__((address_space(1)))
; #define WAIT_V(n) asm volatile("s_waitcnt vmcnt(" #n ")" ::: "memory")
; #define BAR __builtin_amdgcn_s_barrier()
; template <int K, int LD = K>
; __device__ __forceinline__ void gemm_main(const GAS bf16* A, const GAS bf16* Bt, int brow, int bcol, f32x4 (&acc)[2][2][4][2]) {
;     ...
;   const int wid = tid_ >> 6, lane = tid_ & 63, wr = wid >> 2, wc = wid & 3, fr = lane & 15, fq = lane >> 4;
; #pragma unroll
;   for (int a = 0; a < 2; ++a)
; #pragma unroll
;     for (int b = 0; b < 2; ++b)
; #pragma unroll
;       for (int m = 0; m < 4; ++m)
; #pragma unroll
;         for (int n = 0; n < 2; ++n) acc[a][b][m][n] = f32x4{0.f, 0.f, 0.f, 0.f};
;   bf16x8 At[4][2], B0[2][2], B1[2][2];
;   unsigned so0, so1;
;   { int r_, c_; stage_rc(tid_ * 16, r_, c_); so0 = (unsigned)(r_ * LD + c_) * 2u; stage_rc(tid_ * 16 + 8192, r_, c_); so1 = (unsigned)(r_ * LD + c_) * 2u; }
;   const GAS char* pA0 = (const GAS char*)A + (long)brow * LD * 2; const GAS char* pA1 = pA0 + (long)HALF * LD * 2;
;   const GAS char* pB0 = (const GAS char*)Bt + (long)bcol * LD * 2; const GAS char* pB1 = pB0 + (long)HALF * LD * 2;
;   asm volatile("" : "+s"(pA0), "+s"(pA1), "+s"(pB0), "+s"(pB1));
;   constexpr int nt = K / BK;
;   static_assert(K % 128 == 0 && K >= 256, "K");
;   if (wr == 1) BAR;
;   WAIT_V(0); BAR;
;   BAR;
.LBB0_883:
	s_or_b64 exec, exec, s[22:23]
	v_bfe_i32 v7, v135, 27, 1
	v_lshlrev_b32_e32 v5, 4, v135
	v_lshrrev_b32_e32 v7, 22, v7
	v_add_u32_e32 v7, v5, v7
	v_and_b32_e32 v7, 0xfffffc00, v7
	v_sub_u32_e32 v7, v5, v7
	v_lshrrev_b32_e32 v8, 4, v7
	v_bitop3_b32 v8, v8, v7, 32 bitop3:0x6c
	v_ashrrev_i32_e32 v7, 31, v7
	v_ashrrev_i32_e32 v6, 31, v135
	v_lshrrev_b32_e32 v7, 26, v7
	v_lshrrev_b32_e32 v6, 26, v6
	v_add_u32_e32 v7, v8, v7
	v_add_u32_e32 v6, v135, v6
	v_ashrrev_i32_e32 v7, 6, v7
	v_ashrrev_i32_e32 v6, 6, v6
	v_mul_i32_i24_e32 v10, 64, v7
	v_lshlrev_b32_e32 v9, 3, v6
	v_lshlrev_b32_e32 v6, 5, v6
	v_sub_u32_e32 v8, v8, v10
	v_and_b32_e32 v9, 0x1ffff0, v9
	v_and_b32_e32 v6, 32, v6
	v_ashrrev_i16_sdwa v8, v1, sext(v8) dst_sel:DWORD dst_unused:UNUSED_PAD src0_sel:DWORD src1_sel:BYTE_0
	v_add_u32_sdwa v6, v6, sext(v8) dst_sel:DWORD dst_unused:UNUSED_PAD src0_sel:DWORD src1_sel:WORD_0
	v_add_lshl_u32 v7, v7, v9, 11
	v_lshl_add_u32 v130, v6, 1, v7
	v_add_u32_e32 v6, 0x2000, v5
	v_ashrrev_i32_e32 v7, 31, v6
	v_lshrrev_b32_e32 v7, 22, v7
	v_add_u32_e32 v7, v6, v7
	v_ashrrev_i32_e32 v7, 10, v7
	v_mul_i32_i24_e32 v8, 0x400, v7
	v_sub_u32_e32 v6, v6, v8
	v_lshrrev_b32_e32 v8, 4, v6
	v_bitop3_b32 v6, v8, v6, 32 bitop3:0x6c
	v_ashrrev_i32_e32 v9, 31, v6
	v_lshrrev_b32_e32 v9, 26, v9
	v_add_u32_e32 v9, v6, v9
	v_lshrrev_b32_e32 v10, 6, v9
	v_and_b32_e32 v9, 0xc0, v9
	v_lshlrev_b32_e32 v8, 3, v7
	v_lshlrev_b32_e32 v7, 5, v7
	v_sub_u32_e32 v6, v6, v9
	v_and_b32_e32 v8, 0x1ffff0, v8
	v_and_b32_e32 v7, 32, v7
	v_ashrrev_i16_sdwa v6, v1, sext(v6) dst_sel:DWORD dst_unused:UNUSED_PAD src0_sel:DWORD src1_sel:BYTE_0
	v_add_u32_sdwa v6, v7, sext(v6) dst_sel:DWORD dst_unused:UNUSED_PAD src0_sel:DWORD src1_sel:WORD_0
	v_add_lshl_u32 v7, v10, v8, 11
	v_and_b32_e32 v3, 15, v135
	v_lshl_add_u32 v132, v6, 1, v7
	v_lshlrev_b32_e32 v6, 2, v135
	v_and_b32_e32 v4, 48, v135
	v_lshlrev_b32_e32 v3, 6, v3
	v_and_b32_e32 v6, 32, v6
	v_lshlrev_b32_e32 v11, 6, v135
	v_bitop3_b32 v3, v3, v6, v4 bitop3:0x36
	v_lshlrev_b32_e32 v13, 13, v2
	v_and_or_b32 v2, v11, s38, v4
	v_add_u32_e32 v7, s29, v3
	v_add_u32_e32 v8, s30, v3
	v_add_u32_e32 v9, s31, v3
	v_add_u32_e32 v10, s33, v3
	v_and_b32_e32 v12, 0x3000, v11
	v_add_u32_e32 v3, 0x100, v3
	v_xad_u32 v4, v2, v6, s34
	v_or_b32_e32 v6, 0x800, v13
	v_or_b32_e32 v11, 0x1000, v13
	v_or_b32_e32 v14, 0x1800, v13
	v_mov_b32_e32 v2, 0
	v_add_u32_e32 v146, 0x100, v5
	v_add_u32_e32 v152, s29, v5
	v_add_u32_e32 v154, s30, v5
	v_add_u32_e32 v156, s31, v5
	v_add_u32_e32 v158, s33, v5
	v_mov_b32_e32 v133, v131
	s_mov_b32 s15, -2
	v_add_u32_e32 v145, v7, v12
	v_add_u32_e32 v139, v3, v13
	v_add_u32_e32 v138, v4, v6
	v_add_u32_e32 v137, v4, v11
	v_add_u32_e32 v136, v4, v14
	v_add_u32_e32 v144, 0xc000, v146
	v_add_u32_e32 v143, 0xe000, v146
	v_add_u32_e32 v142, v8, v12
	v_add_u32_e32 v147, 0x2000, v146
	v_add_u32_e32 v141, v9, v12
	v_add_u32_e32 v148, 0x4000, v146
	v_add_u32_e32 v149, 0x6000, v146
	v_add_u32_e32 v140, v10, v12
	v_add_u32_e32 v150, 0x8000, v146
	v_add_u32_e32 v151, 0xa000, v146
	v_add_u32_e32 v153, 0x2000, v152
	v_add_u32_e32 v155, 0x2000, v154
	v_add_u32_e32 v157, 0x2000, v156
	v_add_u32_e32 v159, 0x2000, v158
	v_mov_b32_e32 v3, v2
	v_mov_b32_e32 v4, v2
	v_mov_b32_e32 v5, v2
	v_mov_b32_e32 v6, v2
	v_mov_b32_e32 v7, v2
	v_mov_b32_e32 v8, v2
	v_mov_b32_e32 v9, v2
	v_mov_b32_e32 v10, v2
	v_mov_b32_e32 v11, v2
	v_mov_b32_e32 v12, v2
	v_mov_b32_e32 v13, v2
	v_mov_b32_e32 v14, v2
	v_mov_b32_e32 v15, v2
	v_mov_b32_e32 v16, v2
	v_mov_b32_e32 v17, v2
	v_mov_b32_e32 v18, v2
	v_mov_b32_e32 v19, v2
	v_mov_b32_e32 v20, v2
	v_mov_b32_e32 v21, v2
	v_mov_b32_e32 v22, v2
	v_mov_b32_e32 v23, v2
	v_mov_b32_e32 v24, v2
	v_mov_b32_e32 v25, v2
	v_mov_b32_e32 v26, v2
	v_mov_b32_e32 v27, v2
	v_mov_b32_e32 v28, v2
	v_mov_b32_e32 v29, v2
	v_mov_b32_e32 v30, v2
	v_mov_b32_e32 v31, v2
	v_mov_b32_e32 v32, v2
	v_mov_b32_e32 v33, v2
	v_mov_b32_e32 v34, v2
	v_mov_b32_e32 v35, v2
	v_mov_b32_e32 v36, v2
	v_mov_b32_e32 v37, v2
	v_mov_b32_e32 v38, v2
	v_mov_b32_e32 v39, v2
	v_mov_b32_e32 v40, v2
	v_mov_b32_e32 v41, v2
	v_mov_b32_e32 v42, v2
	v_mov_b32_e32 v43, v2
	v_mov_b32_e32 v44, v2
	v_mov_b32_e32 v45, v2
	v_mov_b32_e32 v46, v2
	v_mov_b32_e32 v47, v2
	v_mov_b32_e32 v48, v2
	v_mov_b32_e32 v49, v2
	v_mov_b32_e32 v50, v2
	v_mov_b32_e32 v51, v2
	v_mov_b32_e32 v52, v2
	v_mov_b32_e32 v53, v2
	v_mov_b32_e32 v54, v2
	v_mov_b32_e32 v55, v2
	v_mov_b32_e32 v56, v2
	v_mov_b32_e32 v57, v2
	v_mov_b32_e32 v58, v2
	v_mov_b32_e32 v59, v2
	v_mov_b32_e32 v60, v2
	v_mov_b32_e32 v61, v2
	v_mov_b32_e32 v62, v2
	v_mov_b32_e32 v63, v2
	v_mov_b32_e32 v64, v2
	v_mov_b32_e32 v65, v2
	v_mov_b32_e32 v66, v2
	v_mov_b32_e32 v67, v2
	v_mov_b32_e32 v68, v2
	v_mov_b32_e32 v69, v2
	v_mov_b32_e32 v70, v2
	v_mov_b32_e32 v71, v2
	v_mov_b32_e32 v72, v2
	v_mov_b32_e32 v73, v2
	v_mov_b32_e32 v74, v2
	v_mov_b32_e32 v75, v2
	v_mov_b32_e32 v76, v2
	v_mov_b32_e32 v77, v2
	v_mov_b32_e32 v78, v2
	v_mov_b32_e32 v79, v2
	v_mov_b32_e32 v80, v2
	v_mov_b32_e32 v81, v2
	v_mov_b32_e32 v82, v2
	v_mov_b32_e32 v83, v2
	v_mov_b32_e32 v84, v2
	v_mov_b32_e32 v85, v2
	v_mov_b32_e32 v86, v2
	v_mov_b32_e32 v87, v2
	v_mov_b32_e32 v88, v2
	v_mov_b32_e32 v89, v2
	v_mov_b32_e32 v90, v2
	v_mov_b32_e32 v91, v2
	v_mov_b32_e32 v92, v2
	v_mov_b32_e32 v93, v2
	v_mov_b32_e32 v94, v2
	v_mov_b32_e32 v95, v2
	v_mov_b32_e32 v96, v2
	v_mov_b32_e32 v97, v2
	v_mov_b32_e32 v98, v2
	v_mov_b32_e32 v99, v2
	v_mov_b32_e32 v100, v2
	v_mov_b32_e32 v101, v2
	v_mov_b32_e32 v102, v2
	v_mov_b32_e32 v103, v2
	v_mov_b32_e32 v104, v2
	v_mov_b32_e32 v105, v2
	v_mov_b32_e32 v106, v2
	v_mov_b32_e32 v107, v2
	v_mov_b32_e32 v108, v2
	v_mov_b32_e32 v109, v2
	v_mov_b32_e32 v110, v2
	v_mov_b32_e32 v111, v2
	v_mov_b32_e32 v112, v2
	v_mov_b32_e32 v113, v2
	v_mov_b32_e32 v114, v2
	v_mov_b32_e32 v115, v2
	v_mov_b32_e32 v116, v2
	v_mov_b32_e32 v117, v2
	v_mov_b32_e32 v118, v2
	v_mov_b32_e32 v119, v2
	v_mov_b32_e32 v120, v2
	v_mov_b32_e32 v121, v2
	v_mov_b32_e32 v122, v2
	v_mov_b32_e32 v123, v2
	v_mov_b32_e32 v124, v2
	v_mov_b32_e32 v125, v2
	v_mov_b32_e32 v126, v2
	v_mov_b32_e32 v127, v2
	v_mov_b32_e32 v128, v2
	v_mov_b32_e32 v129, v2
	s_waitcnt vmcnt(0)
	s_barrier
	s_barrier
	.p2align 6

; #define GAS __attribute__((address_space(1)))
; #define WAIT_V(n) asm volatile("s_waitcnt vmcnt(" #n ")" ::: "memory")
; #define BAR __builtin_amdgcn_s_barrier()
; template <int K, int LD = K>
; __device__ __forceinline__ void gemm_main(const GAS bf16* A, const GAS bf16* Bt, int brow, int bcol, f32x4 (&acc)[2][2][4][2]) {
;     ...
;   const int wid = tid_ >> 6, lane = tid_ & 63, wr = wid >> 2, wc = wid & 3, fr = lane & 15, fq = lane >> 4;
; #pragma unroll
;   for (int a = 0; a < 2; ++a)
; #pragma unroll
;     for (int b = 0; b < 2; ++b)
; #pragma unroll
;       for (int m = 0; m < 4; ++m)
; #pragma unroll
;         for (int n = 0; n < 2; ++n) acc[a][b][m][n] = f32x4{0.f, 0.f, 0.f, 0.f};
;   bf16x8 At[4][2], B0[2][2], B1[2][2];
;   unsigned so0, so1;
;   { int r_, c_; stage_rc(tid_ * 16, r_, c_); so0 = (unsigned)(r_ * LD + c_) * 2u; stage_rc(tid_ * 16 + 8192, r_, c_); so1 = (unsigned)(r_ * LD + c_) * 2u; }
;   const GAS char* pA0 = (const GAS char*)A + (long)brow * LD * 2; const GAS char* pA1 = pA0 + (long)HALF * LD * 2;
;   const GAS char* pB0 = (const GAS char*)Bt + (long)bcol * LD * 2; const GAS char* pB1 = pB0 + (long)HALF * LD * 2;
;   asm volatile("" : "+s"(pA0), "+s"(pA1), "+s"(pB0), "+s"(pB1));
;   constexpr int nt = K / BK;
;   static_assert(K % 128 == 0 && K >= 256, "K");
;   if (wr == 1) BAR;
;   WAIT_V(0); BAR;
;   BAR;
.LBB0_1104:
	s_or_b64 exec, exec, s[22:23]
	v_bfe_i32 v7, v134, 27, 1
	v_lshlrev_b32_e32 v5, 4, v134
	v_lshrrev_b32_e32 v7, 22, v7
	v_add_u32_e32 v7, v5, v7
	v_and_b32_e32 v7, 0xfffffc00, v7
	v_ashrrev_i32_e32 v6, 31, v134
	v_sub_u32_e32 v7, v5, v7
	v_lshrrev_b32_e32 v6, 26, v6
	v_lshrrev_b32_e32 v8, 4, v7
	v_add_u32_e32 v6, v134, v6
	v_bitop3_b32 v8, v8, v7, 32 bitop3:0x6c
	v_ashrrev_i32_e32 v7, 31, v7
	v_ashrrev_i32_e32 v6, 6, v6
	v_lshrrev_b32_e32 v7, 26, v7
	v_lshlrev_b32_e32 v9, 3, v6
	v_add_u32_e32 v7, v8, v7
	v_and_b32_e32 v9, 0x3fffff0, v9
	v_ashrrev_i32_e32 v7, 6, v7
	v_add_u32_e32 v9, v7, v9
	v_mul_i32_i24_e32 v7, 64, v7
	v_sub_u32_e32 v7, v8, v7
	v_lshlrev_b32_e32 v6, 5, v6
	v_ashrrev_i16_sdwa v7, v1, sext(v7) dst_sel:DWORD dst_unused:UNUSED_PAD src0_sel:DWORD src1_sel:BYTE_0
	v_mul_lo_u32 v8, v9, s31
	v_bfe_i32 v7, v7, 0, 16
	v_and_or_b32 v6, v6, 32, v8
	v_add_lshl_u32 v130, v6, v7, 1
	v_add_u32_e32 v6, 0x2000, v5
	v_ashrrev_i32_e32 v7, 31, v6
	v_lshrrev_b32_e32 v7, 22, v7
	v_add_u32_e32 v7, v6, v7
	v_ashrrev_i32_e32 v7, 10, v7
	v_mul_i32_i24_e32 v8, 0x400, v7
	v_sub_u32_e32 v6, v6, v8
	v_lshrrev_b32_e32 v8, 4, v6
	v_bitop3_b32 v6, v8, v6, 32 bitop3:0x6c
	v_ashrrev_i32_e32 v9, 31, v6
	v_lshrrev_b32_e32 v9, 26, v9
	v_lshlrev_b32_e32 v8, 3, v7
	v_add_u32_e32 v9, v6, v9
	v_and_b32_e32 v8, 0x3fffff0, v8
	v_lshrrev_b32_e32 v10, 6, v9
	v_and_b32_e32 v9, 0xc0, v9
	v_add_u32_e32 v8, v10, v8
	v_sub_u32_e32 v6, v6, v9
	v_lshlrev_b32_e32 v7, 5, v7
	v_ashrrev_i16_sdwa v6, v1, sext(v6) dst_sel:DWORD dst_unused:UNUSED_PAD src0_sel:DWORD src1_sel:BYTE_0
	v_mul_lo_u32 v8, v8, s31
	v_bfe_i32 v6, v6, 0, 16
	v_and_or_b32 v7, v7, 32, v8
	v_and_b32_e32 v3, 15, v134
	v_add_lshl_u32 v132, v7, v6, 1
	v_lshlrev_b32_e32 v6, 2, v134
	v_and_b32_e32 v4, 48, v134
	v_lshlrev_b32_e32 v3, 6, v3
	v_and_b32_e32 v6, 32, v6
	v_lshlrev_b32_e32 v11, 6, v134
	v_bitop3_b32 v3, v3, v6, v4 bitop3:0x36
	v_lshlrev_b32_e32 v13, 13, v2
	v_and_or_b32 v2, v11, s38, v4
	v_add_u32_e32 v7, s34, v3
	v_add_u32_e32 v8, s35, v3
	v_add_u32_e32 v9, s36, v3
	v_add_u32_e32 v10, s37, v3
	v_and_b32_e32 v12, 0x3000, v11
	v_add_u32_e32 v3, 0x100, v3
	v_xad_u32 v4, v2, v6, s33
	v_or_b32_e32 v6, 0x800, v13
	v_or_b32_e32 v11, 0x1000, v13
	v_or_b32_e32 v14, 0x1800, v13
	v_mov_b32_e32 v2, 0
	v_add_u32_e32 v145, 0x100, v5
	v_add_u32_e32 v151, s34, v5
	v_add_u32_e32 v153, s35, v5
	v_add_u32_e32 v155, s36, v5
	v_add_u32_e32 v157, s37, v5
	v_mov_b32_e32 v133, v131
	s_mov_b32 s22, -2
	v_add_u32_e32 v144, v7, v12
	v_add_u32_e32 v138, v3, v13
	v_add_u32_e32 v137, v4, v6
	v_add_u32_e32 v136, v4, v11
	v_add_u32_e32 v135, v4, v14
	v_add_u32_e32 v143, 0xc000, v145
	v_add_u32_e32 v142, 0xe000, v145
	v_add_u32_e32 v141, v8, v12
	v_add_u32_e32 v146, 0x2000, v145
	v_add_u32_e32 v140, v9, v12
	v_add_u32_e32 v147, 0x4000, v145
	v_add_u32_e32 v148, 0x6000, v145
	v_add_u32_e32 v139, v10, v12
	v_add_u32_e32 v149, 0x8000, v145
	v_add_u32_e32 v150, 0xa000, v145
	v_add_u32_e32 v152, 0x2000, v151
	v_add_u32_e32 v154, 0x2000, v153
	v_add_u32_e32 v156, 0x2000, v155
	v_add_u32_e32 v158, 0x2000, v157
	v_mov_b32_e32 v3, v2
	v_mov_b32_e32 v4, v2
	v_mov_b32_e32 v5, v2
	v_mov_b32_e32 v6, v2
	v_mov_b32_e32 v7, v2
	v_mov_b32_e32 v8, v2
	v_mov_b32_e32 v9, v2
	v_mov_b32_e32 v10, v2
	v_mov_b32_e32 v11, v2
	v_mov_b32_e32 v12, v2
	v_mov_b32_e32 v13, v2
	v_mov_b32_e32 v14, v2
	v_mov_b32_e32 v15, v2
	v_mov_b32_e32 v16, v2
	v_mov_b32_e32 v17, v2
	v_mov_b32_e32 v18, v2
	v_mov_b32_e32 v19, v2
	v_mov_b32_e32 v20, v2
	v_mov_b32_e32 v21, v2
	v_mov_b32_e32 v22, v2
	v_mov_b32_e32 v23, v2
	v_mov_b32_e32 v24, v2
	v_mov_b32_e32 v25, v2
	v_mov_b32_e32 v26, v2
	v_mov_b32_e32 v27, v2
	v_mov_b32_e32 v28, v2
	v_mov_b32_e32 v29, v2
	v_mov_b32_e32 v30, v2
	v_mov_b32_e32 v31, v2
	v_mov_b32_e32 v32, v2
	v_mov_b32_e32 v33, v2
	v_mov_b32_e32 v34, v2
	v_mov_b32_e32 v35, v2
	v_mov_b32_e32 v36, v2
	v_mov_b32_e32 v37, v2
	v_mov_b32_e32 v38, v2
	v_mov_b32_e32 v39, v2
	v_mov_b32_e32 v40, v2
	v_mov_b32_e32 v41, v2
	v_mov_b32_e32 v42, v2
	v_mov_b32_e32 v43, v2
	v_mov_b32_e32 v44, v2
	v_mov_b32_e32 v45, v2
	v_mov_b32_e32 v46, v2
	v_mov_b32_e32 v47, v2
	v_mov_b32_e32 v48, v2
	v_mov_b32_e32 v49, v2
	v_mov_b32_e32 v50, v2
	v_mov_b32_e32 v51, v2
	v_mov_b32_e32 v52, v2
	v_mov_b32_e32 v53, v2
	v_mov_b32_e32 v54, v2
	v_mov_b32_e32 v55, v2
	v_mov_b32_e32 v56, v2
	v_mov_b32_e32 v57, v2
	v_mov_b32_e32 v58, v2
	v_mov_b32_e32 v59, v2
	v_mov_b32_e32 v60, v2
	v_mov_b32_e32 v61, v2
	v_mov_b32_e32 v62, v2
	v_mov_b32_e32 v63, v2
	v_mov_b32_e32 v64, v2
	v_mov_b32_e32 v65, v2
	v_mov_b32_e32 v66, v2
	v_mov_b32_e32 v67, v2
	v_mov_b32_e32 v68, v2
	v_mov_b32_e32 v69, v2
	v_mov_b32_e32 v70, v2
	v_mov_b32_e32 v71, v2
	v_mov_b32_e32 v72, v2
	v_mov_b32_e32 v73, v2
	v_mov_b32_e32 v74, v2
	v_mov_b32_e32 v75, v2
	v_mov_b32_e32 v76, v2
	v_mov_b32_e32 v77, v2
	v_mov_b32_e32 v78, v2
	v_mov_b32_e32 v79, v2
	v_mov_b32_e32 v80, v2
	v_mov_b32_e32 v81, v2
	v_mov_b32_e32 v82, v2
	v_mov_b32_e32 v83, v2
	v_mov_b32_e32 v84, v2
	v_mov_b32_e32 v85, v2
	v_mov_b32_e32 v86, v2
	v_mov_b32_e32 v87, v2
	v_mov_b32_e32 v88, v2
	v_mov_b32_e32 v89, v2
	v_mov_b32_e32 v90, v2
	v_mov_b32_e32 v91, v2
	v_mov_b32_e32 v92, v2
	v_mov_b32_e32 v93, v2
	v_mov_b32_e32 v94, v2
	v_mov_b32_e32 v95, v2
	v_mov_b32_e32 v96, v2
	v_mov_b32_e32 v97, v2
	v_mov_b32_e32 v98, v2
	v_mov_b32_e32 v99, v2
	v_mov_b32_e32 v100, v2
	v_mov_b32_e32 v101, v2
	v_mov_b32_e32 v102, v2
	v_mov_b32_e32 v103, v2
	v_mov_b32_e32 v104, v2
	v_mov_b32_e32 v105, v2
	v_mov_b32_e32 v106, v2
	v_mov_b32_e32 v107, v2
	v_mov_b32_e32 v108, v2
	v_mov_b32_e32 v109, v2
	v_mov_b32_e32 v110, v2
	v_mov_b32_e32 v111, v2
	v_mov_b32_e32 v112, v2
	v_mov_b32_e32 v113, v2
	v_mov_b32_e32 v114, v2
	v_mov_b32_e32 v115, v2
	v_mov_b32_e32 v116, v2
	v_mov_b32_e32 v117, v2
	v_mov_b32_e32 v118, v2
	v_mov_b32_e32 v119, v2
	v_mov_b32_e32 v120, v2
	v_mov_b32_e32 v121, v2
	v_mov_b32_e32 v122, v2
	v_mov_b32_e32 v123, v2
	v_mov_b32_e32 v124, v2
	v_mov_b32_e32 v125, v2
	v_mov_b32_e32 v126, v2
	v_mov_b32_e32 v127, v2
	v_mov_b32_e32 v128, v2
	v_mov_b32_e32 v129, v2
	s_waitcnt vmcnt(0)
	s_barrier
	s_barrier
	.p2align 6

; #define GAS __attribute__((address_space(1)))
; #define WAIT_V(n) asm volatile("s_waitcnt vmcnt(" #n ")" ::: "memory")
; #define BAR __builtin_amdgcn_s_barrier()
; template <int K, int LD = K>
; __device__ __forceinline__ void gemm_main(const GAS bf16* A, const GAS bf16* Bt, int brow, int bcol, f32x4 (&acc)[2][2][4][2]) {
;     ...
;   const int wid = tid_ >> 6, lane = tid_ & 63, wr = wid >> 2, wc = wid & 3, fr = lane & 15, fq = lane >> 4;
; #pragma unroll
;   for (int a = 0; a < 2; ++a)
; #pragma unroll
;     for (int b = 0; b < 2; ++b)
; #pragma unroll
;       for (int m = 0; m < 4; ++m)
; #pragma unroll
;         for (int n = 0; n < 2; ++n) acc[a][b][m][n] = f32x4{0.f, 0.f, 0.f, 0.f};
;   bf16x8 At[4][2], B0[2][2], B1[2][2];
;   unsigned so0, so1;
;   { int r_, c_; stage_rc(tid_ * 16, r_, c_); so0 = (unsigned)(r_ * LD + c_) * 2u; stage_rc(tid_ * 16 + 8192, r_, c_); so1 = (unsigned)(r_ * LD + c_) * 2u; }
;   const GAS char* pA0 = (const GAS char*)A + (long)brow * LD * 2; const GAS char* pA1 = pA0 + (long)HALF * LD * 2;
;   const GAS char* pB0 = (const GAS char*)Bt + (long)bcol * LD * 2; const GAS char* pB1 = pB0 + (long)HALF * LD * 2;
;   asm volatile("" : "+s"(pA0), "+s"(pA1), "+s"(pB0), "+s"(pB1));
;   constexpr int nt = K / BK;
;   static_assert(K % 128 == 0 && K >= 256, "K");
;   if (wr == 1) BAR;
;   WAIT_V(0); BAR;
;   BAR;
.LBB0_1225:
	s_or_b64 exec, exec, s[30:31]
	v_bfe_i32 v6, v132, 27, 1
	v_lshlrev_b32_e32 v141, 4, v132
	v_lshrrev_b32_e32 v6, 22, v6
	v_add_u32_e32 v6, v141, v6
	v_and_b32_e32 v6, 0xfffffc00, v6
	v_sub_u32_e32 v6, v141, v6
	v_lshrrev_b32_e32 v7, 4, v6
	v_bitop3_b32 v7, v7, v6, 32 bitop3:0x6c
	v_ashrrev_i32_e32 v6, 31, v6
	v_ashrrev_i32_e32 v5, 31, v132
	v_lshrrev_b32_e32 v6, 26, v6
	v_lshrrev_b32_e32 v5, 26, v5
	v_add_u32_e32 v6, v7, v6
	v_add_u32_e32 v5, v132, v5
	v_ashrrev_i32_e32 v6, 6, v6
	v_ashrrev_i32_e32 v5, 6, v5
	v_mul_i32_i24_e32 v9, 64, v6
	v_lshlrev_b32_e32 v8, 3, v5
	v_lshlrev_b32_e32 v5, 5, v5
	v_sub_u32_e32 v7, v7, v9
	v_and_b32_e32 v8, 0x1ffff0, v8
	v_and_b32_e32 v5, 32, v5
	v_ashrrev_i16_sdwa v7, v1, sext(v7) dst_sel:DWORD dst_unused:UNUSED_PAD src0_sel:DWORD src1_sel:BYTE_0
	v_add_u32_sdwa v5, v5, sext(v7) dst_sel:DWORD dst_unused:UNUSED_PAD src0_sel:DWORD src1_sel:WORD_0
	v_add_lshl_u32 v6, v6, v8, 11
	v_lshl_add_u32 v138, v5, 1, v6
	v_add_u32_e32 v5, 0x2000, v141
	v_ashrrev_i32_e32 v6, 31, v5
	v_lshrrev_b32_e32 v6, 22, v6
	v_add_u32_e32 v6, v5, v6
	v_ashrrev_i32_e32 v6, 10, v6
	v_mul_i32_i24_e32 v7, 0x400, v6
	v_sub_u32_e32 v5, v5, v7
	v_lshrrev_b32_e32 v7, 4, v5
	v_bitop3_b32 v5, v7, v5, 32 bitop3:0x6c
	v_ashrrev_i32_e32 v8, 31, v5
	v_lshrrev_b32_e32 v8, 26, v8
	v_add_u32_e32 v8, v5, v8
	v_lshrrev_b32_e32 v9, 6, v8
	v_and_b32_e32 v8, 0xc0, v8
	v_lshlrev_b32_e32 v7, 3, v6
	v_lshlrev_b32_e32 v6, 5, v6
	v_sub_u32_e32 v5, v5, v8
	v_and_b32_e32 v7, 0x1ffff0, v7
	v_and_b32_e32 v6, 32, v6
	v_ashrrev_i16_sdwa v5, v1, sext(v5) dst_sel:DWORD dst_unused:UNUSED_PAD src0_sel:DWORD src1_sel:BYTE_0
	v_add_u32_sdwa v5, v6, sext(v5) dst_sel:DWORD dst_unused:UNUSED_PAD src0_sel:DWORD src1_sel:WORD_0
	v_add_lshl_u32 v6, v9, v7, 11
	v_and_b32_e32 v3, 15, v132
	v_lshl_add_u32 v130, v5, 1, v6
	v_lshlrev_b32_e32 v5, 2, v132
	v_and_b32_e32 v4, 48, v132
	v_lshlrev_b32_e32 v3, 6, v3
	v_and_b32_e32 v5, 32, v5
	v_lshlrev_b32_e32 v10, 6, v132
	v_bitop3_b32 v3, v3, v5, v4 bitop3:0x36
	v_lshlrev_b32_e32 v12, 13, v2
	v_and_or_b32 v2, v10, s46, v4
	v_add_u32_e32 v6, s38, v3
	v_add_u32_e32 v7, s39, v3
	v_add_u32_e32 v8, s40, v3
	v_add_u32_e32 v9, s41, v3
	v_and_b32_e32 v11, 0x3000, v10
	v_add_u32_e32 v3, 0x100, v3
	v_xad_u32 v4, v2, v5, s42
	v_or_b32_e32 v5, 0x800, v12
	v_or_b32_e32 v10, 0x1000, v12
	v_or_b32_e32 v13, 0x1800, v12
	v_mov_b32_e32 v2, 0
	v_mov_b32_e32 v131, v139
	s_mov_b32 s21, -2
	v_add_u32_e32 v143, v6, v11
	v_add_u32_e32 v136, v3, v12
	v_add_u32_e32 v135, v4, v5
	v_add_u32_e32 v134, v4, v10
	v_add_u32_e32 v133, v4, v13
	v_add_u32_e32 v142, v7, v11
	v_add_u32_e32 v140, v8, v11
	v_add_u32_e32 v137, v9, v11
	v_mov_b32_e32 v3, v2
	v_mov_b32_e32 v4, v2
	v_mov_b32_e32 v5, v2
	v_mov_b32_e32 v6, v2
	v_mov_b32_e32 v7, v2
	v_mov_b32_e32 v8, v2
	v_mov_b32_e32 v9, v2
	v_mov_b32_e32 v10, v2
	v_mov_b32_e32 v11, v2
	v_mov_b32_e32 v12, v2
	v_mov_b32_e32 v13, v2
	v_mov_b32_e32 v14, v2
	v_mov_b32_e32 v15, v2
	v_mov_b32_e32 v16, v2
	v_mov_b32_e32 v17, v2
	v_mov_b32_e32 v18, v2
	v_mov_b32_e32 v19, v2
	v_mov_b32_e32 v20, v2
	v_mov_b32_e32 v21, v2
	v_mov_b32_e32 v22, v2
	v_mov_b32_e32 v23, v2
	v_mov_b32_e32 v24, v2
	v_mov_b32_e32 v25, v2
	v_mov_b32_e32 v26, v2
	v_mov_b32_e32 v27, v2
	v_mov_b32_e32 v28, v2
	v_mov_b32_e32 v29, v2
	v_mov_b32_e32 v30, v2
	v_mov_b32_e32 v31, v2
	v_mov_b32_e32 v32, v2
	v_mov_b32_e32 v33, v2
	v_mov_b32_e32 v34, v2
	v_mov_b32_e32 v35, v2
	v_mov_b32_e32 v36, v2
	v_mov_b32_e32 v37, v2
	v_mov_b32_e32 v38, v2
	v_mov_b32_e32 v39, v2
	v_mov_b32_e32 v40, v2
	v_mov_b32_e32 v41, v2
	v_mov_b32_e32 v42, v2
	v_mov_b32_e32 v43, v2
	v_mov_b32_e32 v44, v2
	v_mov_b32_e32 v45, v2
	v_mov_b32_e32 v46, v2
	v_mov_b32_e32 v47, v2
	v_mov_b32_e32 v48, v2
	v_mov_b32_e32 v49, v2
	v_mov_b32_e32 v50, v2
	v_mov_b32_e32 v51, v2
	v_mov_b32_e32 v52, v2
	v_mov_b32_e32 v53, v2
	v_mov_b32_e32 v54, v2
	v_mov_b32_e32 v55, v2
	v_mov_b32_e32 v56, v2
	v_mov_b32_e32 v57, v2
	v_mov_b32_e32 v58, v2
	v_mov_b32_e32 v59, v2
	v_mov_b32_e32 v60, v2
	v_mov_b32_e32 v61, v2
	v_mov_b32_e32 v62, v2
	v_mov_b32_e32 v63, v2
	v_mov_b32_e32 v64, v2
	v_mov_b32_e32 v65, v2
	v_mov_b32_e32 v66, v2
	v_mov_b32_e32 v67, v2
	v_mov_b32_e32 v68, v2
	v_mov_b32_e32 v69, v2
	v_mov_b32_e32 v70, v2
	v_mov_b32_e32 v71, v2
	v_mov_b32_e32 v72, v2
	v_mov_b32_e32 v73, v2
	v_mov_b32_e32 v74, v2
	v_mov_b32_e32 v75, v2
	v_mov_b32_e32 v76, v2
	v_mov_b32_e32 v77, v2
	v_mov_b32_e32 v78, v2
	v_mov_b32_e32 v79, v2
	v_mov_b32_e32 v80, v2
	v_mov_b32_e32 v81, v2
	v_mov_b32_e32 v82, v2
	v_mov_b32_e32 v83, v2
	v_mov_b32_e32 v84, v2
	v_mov_b32_e32 v85, v2
	v_mov_b32_e32 v86, v2
	v_mov_b32_e32 v87, v2
	v_mov_b32_e32 v88, v2
	v_mov_b32_e32 v89, v2
	v_mov_b32_e32 v90, v2
	v_mov_b32_e32 v91, v2
	v_mov_b32_e32 v92, v2
	v_mov_b32_e32 v93, v2
	v_mov_b32_e32 v94, v2
	v_mov_b32_e32 v95, v2
	v_mov_b32_e32 v96, v2
	v_mov_b32_e32 v97, v2
	v_mov_b32_e32 v98, v2
	v_mov_b32_e32 v99, v2
	v_mov_b32_e32 v100, v2
	v_mov_b32_e32 v101, v2
	v_mov_b32_e32 v102, v2
	v_mov_b32_e32 v103, v2
	v_mov_b32_e32 v104, v2
	v_mov_b32_e32 v105, v2
	v_mov_b32_e32 v106, v2
	v_mov_b32_e32 v107, v2
	v_mov_b32_e32 v108, v2
	v_mov_b32_e32 v109, v2
	v_mov_b32_e32 v110, v2
	v_mov_b32_e32 v111, v2
	v_mov_b32_e32 v112, v2
	v_mov_b32_e32 v113, v2
	v_mov_b32_e32 v114, v2
	v_mov_b32_e32 v115, v2
	v_mov_b32_e32 v116, v2
	v_mov_b32_e32 v117, v2
	v_mov_b32_e32 v118, v2
	v_mov_b32_e32 v119, v2
	v_mov_b32_e32 v120, v2
	v_mov_b32_e32 v121, v2
	v_mov_b32_e32 v122, v2
	v_mov_b32_e32 v123, v2
	v_mov_b32_e32 v124, v2
	v_mov_b32_e32 v125, v2
	v_mov_b32_e32 v126, v2
	v_mov_b32_e32 v127, v2
	v_mov_b32_e32 v128, v2
	v_mov_b32_e32 v129, v2
	s_waitcnt vmcnt(0)
	s_barrier
	s_barrier
	.p2align 6
